# diff epilogue: sixteen 8-byte row-per-lane stores paired through v_permlane32_swap into eight 16-byte stores
# speedup vs baseline: 1.0139x; 1.0081x over previous
; DI float bflo(unsigned u) { return __uint_as_float(u << 16); }
; DI float bfhi(unsigned u) { return __uint_as_float(u & 0xffff0000u); }
; DI float silu_f(float z) { return z / (1.f + __expf(-z)); }
; DI void diff_item(const Params& P, char* lds, int layer, int pair, int qt, int& tab_head) {
;     ...
;     __syncthreads();
;     if (mp == 0) {
;         const float lam = ((const float*)(P.ws + WS_LAM))[layer];
;         const float lam_init = 0.8f - 0.6f * expf(-0.3f * (float)layer);
;         float ss = 0.f;
; #pragma unroll
;         for (int dt = 0; dt < 4; ++dt)
; #pragma unroll
;             for (int i = 0; i < 16; ++i) {
;                 float o = O[dt][i] * inv - lam * cmb[(qs * 128 + 32 * dt + (i & 3) + 8 * (i >> 2) + 4 * hh) * 32 + r];
;                 O[dt][i] = o; ss += o * o;
;             }
;         ss = xhalf_sum(ss);
;         const float rstd = rsqrtf(ss * (1.f / 128.f) + EPS) * (1.f - lam_init);
;         const float* gs = P.g_sub + layer * 128;
;         u16* orow = base + (size_t)qpos * PO;
; #pragma unroll
;         for (int dt = 0; dt < 4; ++dt)
; #pragma unroll
;             for (int g = 0; g < 4; ++g) {
;                 const int d = 32 * dt + 8 * g + 4 * hh;
;                 u32x2 zz = *(const u32x2*)(orow + OFF_Z + 1536 + head * 128 + d);
;                 f32x4 gg = *(const f32x4*)(gs + d);
;                 float y0 = O[dt][4 * g + 0] * rstd * gg.x * silu_f(bflo(zz.x)), y1 = O[dt][4 * g + 1] * rstd * gg.y * silu_f(bfhi(zz.x));
;                 float y2 = O[dt][4 * g + 2] * rstd * gg.z * silu_f(bflo(zz.y)), y3 = O[dt][4 * g + 3] * rstd * gg.w * silu_f(bfhi(zz.y));
.LBB0_268:
	s_or_b64 exec, exec, s[0:1]
	s_movk_i32 s0, 0x100
	v_cmp_gt_u32_e32 vcc, s0, v168
	s_waitcnt lgkmcnt(0)
	s_barrier
	s_and_saveexec_b64 s[40:41], vcc
	s_cbranch_execz .LBB0_197
	v_mov_b64_e32 v[4:5], s[8:9]
	flat_load_dword v12, v[4:5]
	v_lshl_add_u64 v[4:5], v[166:167], 0, s[16:17]
	v_lshlrev_b32_e32 v0, 1, v193
	v_lshl_add_u64 v[4:5], v[4:5], 0, v[0:1]
	s_movk_i32 s0, 0x3000
	v_add_co_u32_e32 v6, vcc, s0, v4
	v_lshlrev_b32_e32 v9, 14, v169
	s_nop 0
	v_addc_co_u32_e32 v7, vcc, 0, v5, vcc
	s_waitcnt vmcnt(0)
	flat_load_dwordx2 v[88:89], v[6:7] offset:768
	v_add3_u32 v2, v3, v9, v2
	ds_read2_b32 v[90:91], v2 offset1:32
	ds_read2_b32 v[92:93], v2 offset0:64 offset1:96
	v_lshlrev_b32_e32 v6, 2, v193
	v_mov_b32_e32 v7, v1
	v_lshl_add_u64 v[6:7], s[10:11], 0, v[6:7]
	v_add_u32_e32 v9, 0x400, v2
	v_add_u32_e32 v10, 0x800, v2
	v_add_u32_e32 v11, 0xc00, v2
	v_add_u32_e32 v13, 0x1000, v2
	v_add_u32_e32 v94, 0x1400, v2
	v_add_u32_e32 v95, 0x1800, v2
	v_add_u32_e32 v96, 0x1c00, v2
	v_add_u32_e32 v97, 0x2000, v2
	v_add_u32_e32 v98, 0x2400, v2
	v_add_u32_e32 v99, 0x2800, v2
	v_add_u32_e32 v100, 0x2c00, v2
	v_add_u32_e32 v101, 0x3000, v2
	v_add_u32_e32 v104, 0x3400, v2
	s_mov_b64 s[0:1], 0x3300
	v_add_u32_e32 v108, 0x3800, v2
	v_add_u32_e32 v109, 0x3c00, v2
	v_lshl_add_u64 v[14:15], v[4:5], 0, s[0:1]
	flat_load_dwordx4 v[2:5], v[6:7]
	ds_read2_b32 v[86:87], v9 offset1:32
	ds_read2_b32 v[84:85], v9 offset0:64 offset1:96
	ds_read2_b32 v[82:83], v10 offset1:32
	ds_read2_b32 v[80:81], v10 offset0:64 offset1:96
	ds_read2_b32 v[144:145], v11 offset1:32
	ds_read2_b32 v[146:147], v11 offset0:64 offset1:96
	ds_read2_b32 v[140:141], v13 offset1:32
	ds_read2_b32 v[142:143], v13 offset0:64 offset1:96
	ds_read2_b32 v[136:137], v94 offset1:32
	ds_read2_b32 v[138:139], v94 offset0:64 offset1:96
	ds_read2_b32 v[132:133], v95 offset1:32
	ds_read2_b32 v[134:135], v95 offset0:64 offset1:96
	ds_read2_b32 v[128:129], v96 offset1:32
	ds_read2_b32 v[130:131], v96 offset0:64 offset1:96
	ds_read2_b32 v[124:125], v97 offset1:32
	ds_read2_b32 v[126:127], v97 offset0:64 offset1:96
	ds_read2_b32 v[120:121], v98 offset1:32
	ds_read2_b32 v[122:123], v98 offset0:64 offset1:96
	ds_read2_b32 v[116:117], v99 offset1:32
	ds_read2_b32 v[118:119], v99 offset0:64 offset1:96
	ds_read2_b32 v[112:113], v100 offset1:32
	ds_read2_b32 v[114:115], v100 offset0:64 offset1:96
	ds_read2_b32 v[106:107], v101 offset1:32
	ds_read2_b32 v[110:111], v101 offset0:64 offset1:96
	ds_read2_b32 v[102:103], v104 offset1:32
	ds_read2_b32 v[104:105], v104 offset0:64 offset1:96
	ds_read2_b32 v[96:97], v108 offset1:32
	ds_read2_b32 v[98:99], v108 offset0:64 offset1:96
	ds_read2_b32 v[94:95], v109 offset1:32
	ds_read2_b32 v[10:11], v109 offset0:64 offset1:96
	s_waitcnt lgkmcnt(0)
	v_pk_mul_f32 v[92:93], v[12:13], v[92:93] op_sel_hi:[0,1]
	v_pk_mul_f32 v[100:101], v[12:13], v[90:91] op_sel_hi:[0,1]
	v_pk_fma_f32 v[90:91], v[66:67], v[8:9], v[92:93] op_sel_hi:[1,0,1] neg_lo:[0,0,1] neg_hi:[0,0,1]
	v_pk_fma_f32 v[92:93], v[64:65], v[8:9], v[100:101] op_sel_hi:[1,0,1] neg_lo:[0,0,1] neg_hi:[0,0,1]
	s_waitcnt vmcnt(0)
	v_lshlrev_b32_e32 v13, 16, v88
	v_and_b32_e32 v88, 0xffff0000, v88
	v_mul_f32_e32 v9, 0xbfb8aa3b, v13
	v_mul_f32_e32 v65, 0xbfb8aa3b, v88
	v_exp_f32_e32 v66, v9
	v_exp_f32_e32 v67, v65
	v_lshlrev_b32_e32 v9, 16, v89
	v_and_b32_e32 v148, 0xffff0000, v89
	v_mul_f32_e32 v64, v93, v93
	v_pk_add_f32 v[66:67], v[66:67], 1.0 op_sel_hi:[1,0]
	v_pk_fma_f32 v[64:65], v[92:93], v[92:93], v[64:65] op_sel_hi:[1,1,0]
	v_div_scale_f32 v89, s[0:1], v67, v67, v88
	v_rcp_f32_e32 v108, v89
	v_div_scale_f32 v101, s[0:1], v66, v66, v13
	v_rcp_f32_e32 v109, v101
	v_fma_f32 v150, -v89, v108, 1.0
	v_div_scale_f32 v100, vcc, v88, v67, v88
	v_fmac_f32_e32 v108, v150, v108
	v_fma_f32 v151, -v101, v109, 1.0
	v_mul_f32_e32 v150, v100, v108
	v_div_scale_f32 v149, s[0:1], v13, v66, v13
	v_fmac_f32_e32 v109, v151, v109
	v_fma_f32 v152, -v89, v150, v100
	v_mul_f32_e32 v151, v149, v109
	v_fmac_f32_e32 v150, v152, v108
	v_fma_f32 v153, -v101, v151, v149
	v_fma_f32 v89, -v89, v150, v100
	v_fmac_f32_e32 v151, v153, v109
	v_div_fmas_f32 v89, v89, v108, v150
	v_fma_f32 v100, -v101, v151, v149
	v_div_fixup_f32 v101, v89, v67, v88
	v_mul_f32_e32 v67, 0xbfb8aa3b, v9
	v_exp_f32_e32 v88, v67
	v_mul_f32_e32 v67, 0xbfb8aa3b, v148
	v_exp_f32_e32 v89, v67
	s_mov_b64 vcc, s[0:1]
	v_div_fmas_f32 v67, v100, v109, v151
	v_div_fixup_f32 v100, v67, v66, v13
	v_pk_add_f32 v[108:109], v[88:89], 1.0 op_sel_hi:[1,0]
	v_pk_fma_f32 v[64:65], v[90:91], v[90:91], v[64:65]
	v_div_scale_f32 v13, s[0:1], v109, v109, v148
	v_rcp_f32_e32 v67, v13
	v_mul_f32_e32 v66, v91, v91
	v_pk_add_f32 v[64:65], v[64:65], v[66:67] op_sel_hi:[1,0]
	v_fma_f32 v66, -v13, v67, 1.0
	v_fmac_f32_e32 v67, v66, v67
	v_div_scale_f32 v66, vcc, v148, v109, v148
	v_mul_f32_e32 v88, v66, v67
	v_fma_f32 v89, -v13, v88, v66
	v_fmac_f32_e32 v88, v89, v67
	v_fma_f32 v13, -v13, v88, v66
	v_div_scale_f32 v66, s[0:1], v108, v108, v9
	v_rcp_f32_e32 v149, v66
	v_div_fmas_f32 v13, v13, v67, v88
	v_div_fixup_f32 v109, v13, v109, v148
	flat_load_dwordx2 v[88:89], v[14:15] offset:16
	v_fma_f32 v13, -v66, v149, 1.0
	v_fmac_f32_e32 v149, v13, v149
	v_div_scale_f32 v13, vcc, v9, v108, v9
	v_mul_f32_e32 v148, v13, v149
	v_fma_f32 v67, -v66, v148, v13
	v_fmac_f32_e32 v148, v67, v149
	v_fma_f32 v150, -v66, v148, v13
	v_pk_mul_f32 v[66:67], v[12:13], v[84:85] op_sel_hi:[0,1]
	v_pk_fma_f32 v[84:85], v[70:71], v[8:9], v[66:67] op_sel_hi:[1,0,1] neg_lo:[0,0,1] neg_hi:[0,0,1]
	v_pk_mul_f32 v[66:67], v[12:13], v[86:87] op_sel_hi:[0,1]
	v_pk_fma_f32 v[86:87], v[68:69], v[8:9], v[66:67] op_sel_hi:[1,0,1] neg_lo:[0,0,1] neg_hi:[0,0,1]
; DI void diff_item(const Params& P, char* lds, int layer, int pair, int qt, int& tab_head) {
;     ...
;             for (int i = 0; i < 16; ++i) {
;                 float o = O[dt][i] * inv - lam * cmb[(qs * 128 + 32 * dt + (i & 3) + 8 * (i >> 2) + 4 * hh) * 32 + r];
;                 O[dt][i] = o; ss += o * o;
	v_pk_mul_f32 v[10:11], v[12:13], v[10:11] op_sel_hi:[0,1]
	v_pk_fma_f32 v[64:65], v[86:87], v[86:87], v[64:65]
	v_mul_f32_e32 v66, v87, v87
	v_pk_add_f32 v[64:65], v[64:65], v[66:67] op_sel_hi:[1,0]
	v_mul_f32_e32 v66, v85, v85
	v_pk_fma_f32 v[64:65], v[84:85], v[84:85], v[64:65]
	v_pk_fma_f32 v[10:11], v[30:31], v[8:9], v[10:11] op_sel_hi:[1,0,1] neg_lo:[0,0,1] neg_hi:[0,0,1]
	v_pk_add_f32 v[64:65], v[64:65], v[66:67] op_sel_hi:[1,0]
	v_pk_mul_f32 v[66:67], v[12:13], v[80:81] op_sel_hi:[0,1]
	v_pk_fma_f32 v[80:81], v[74:75], v[8:9], v[66:67] op_sel_hi:[1,0,1] neg_lo:[0,0,1] neg_hi:[0,0,1]
	v_pk_mul_f32 v[66:67], v[12:13], v[82:83] op_sel_hi:[0,1]
	v_pk_fma_f32 v[82:83], v[72:73], v[8:9], v[66:67] op_sel_hi:[1,0,1] neg_lo:[0,0,1] neg_hi:[0,0,1]
	s_nop 0
	v_pk_fma_f32 v[64:65], v[82:83], v[82:83], v[64:65]
	v_mul_f32_e32 v66, v83, v83
	v_pk_add_f32 v[64:65], v[64:65], v[66:67] op_sel_hi:[1,0]
	v_mul_f32_e32 v66, v81, v81
	v_pk_fma_f32 v[64:65], v[80:81], v[80:81], v[64:65]
	s_nop 0
	v_pk_add_f32 v[64:65], v[64:65], v[66:67] op_sel_hi:[1,0]
	v_pk_mul_f32 v[66:67], v[12:13], v[146:147] op_sel_hi:[0,1]
	v_pk_fma_f32 v[78:79], v[78:79], v[8:9], v[66:67] op_sel_hi:[1,0,1] neg_lo:[0,0,1] neg_hi:[0,0,1]
	v_pk_mul_f32 v[66:67], v[12:13], v[144:145] op_sel_hi:[0,1]
	v_pk_fma_f32 v[76:77], v[76:77], v[8:9], v[66:67] op_sel_hi:[1,0,1] neg_lo:[0,0,1] neg_hi:[0,0,1]
	s_nop 0
	v_pk_fma_f32 v[64:65], v[76:77], v[76:77], v[64:65]
	v_mul_f32_e32 v66, v77, v77
	v_pk_add_f32 v[64:65], v[64:65], v[66:67] op_sel_hi:[1,0]
	v_mul_f32_e32 v66, v79, v79
	v_pk_fma_f32 v[64:65], v[78:79], v[78:79], v[64:65]
	s_nop 0
	v_pk_add_f32 v[64:65], v[64:65], v[66:67] op_sel_hi:[1,0]
	v_pk_mul_f32 v[66:67], v[12:13], v[142:143] op_sel_hi:[0,1]
	v_pk_fma_f32 v[72:73], v[50:51], v[8:9], v[66:67] op_sel_hi:[1,0,1] neg_lo:[0,0,1] neg_hi:[0,0,1]
	v_pk_mul_f32 v[50:51], v[12:13], v[140:141] op_sel_hi:[0,1]
	v_pk_fma_f32 v[74:75], v[48:49], v[8:9], v[50:51] op_sel_hi:[1,0,1] neg_lo:[0,0,1] neg_hi:[0,0,1]
	s_nop 0
	v_pk_fma_f32 v[48:49], v[74:75], v[74:75], v[64:65]
	v_mul_f32_e32 v50, v75, v75
	v_pk_add_f32 v[48:49], v[48:49], v[50:51] op_sel_hi:[1,0]
	v_mul_f32_e32 v50, v73, v73
	v_pk_fma_f32 v[48:49], v[72:73], v[72:73], v[48:49]
	s_nop 0
	v_pk_add_f32 v[48:49], v[48:49], v[50:51] op_sel_hi:[1,0]
	v_pk_mul_f32 v[50:51], v[12:13], v[138:139] op_sel_hi:[0,1]
	v_pk_fma_f32 v[68:69], v[54:55], v[8:9], v[50:51] op_sel_hi:[1,0,1] neg_lo:[0,0,1] neg_hi:[0,0,1]
	v_pk_mul_f32 v[50:51], v[12:13], v[136:137] op_sel_hi:[0,1]
	v_pk_fma_f32 v[70:71], v[52:53], v[8:9], v[50:51] op_sel_hi:[1,0,1] neg_lo:[0,0,1] neg_hi:[0,0,1]
	s_nop 0
	v_pk_fma_f32 v[48:49], v[70:71], v[70:71], v[48:49]
	v_mul_f32_e32 v50, v71, v71
	v_pk_add_f32 v[48:49], v[48:49], v[50:51] op_sel_hi:[1,0]
	v_mul_f32_e32 v50, v69, v69
	v_pk_fma_f32 v[48:49], v[68:69], v[68:69], v[48:49]
	s_nop 0
	v_pk_add_f32 v[48:49], v[48:49], v[50:51] op_sel_hi:[1,0]
	v_pk_mul_f32 v[50:51], v[12:13], v[134:135] op_sel_hi:[0,1]
	v_pk_fma_f32 v[64:65], v[58:59], v[8:9], v[50:51] op_sel_hi:[1,0,1] neg_lo:[0,0,1] neg_hi:[0,0,1]
	v_pk_mul_f32 v[50:51], v[12:13], v[132:133] op_sel_hi:[0,1]
	v_pk_fma_f32 v[66:67], v[56:57], v[8:9], v[50:51] op_sel_hi:[1,0,1] neg_lo:[0,0,1] neg_hi:[0,0,1]
	s_nop 0
	v_pk_fma_f32 v[48:49], v[66:67], v[66:67], v[48:49]
	v_mul_f32_e32 v50, v67, v67
	v_pk_add_f32 v[48:49], v[48:49], v[50:51] op_sel_hi:[1,0]
	v_mul_f32_e32 v50, v65, v65
	v_pk_fma_f32 v[48:49], v[64:65], v[64:65], v[48:49]
	s_nop 0
	v_pk_add_f32 v[48:49], v[48:49], v[50:51] op_sel_hi:[1,0]
	v_pk_mul_f32 v[50:51], v[12:13], v[130:131] op_sel_hi:[0,1]
	v_pk_fma_f32 v[56:57], v[62:63], v[8:9], v[50:51] op_sel_hi:[1,0,1] neg_lo:[0,0,1] neg_hi:[0,0,1]
	v_pk_mul_f32 v[50:51], v[12:13], v[128:129] op_sel_hi:[0,1]
	v_pk_fma_f32 v[58:59], v[60:61], v[8:9], v[50:51] op_sel_hi:[1,0,1] neg_lo:[0,0,1] neg_hi:[0,0,1]
	s_nop 0
	v_pk_fma_f32 v[48:49], v[58:59], v[58:59], v[48:49]
	v_mul_f32_e32 v50, v59, v59
	v_pk_add_f32 v[48:49], v[48:49], v[50:51] op_sel_hi:[1,0]
	v_mul_f32_e32 v50, v57, v57
	v_pk_fma_f32 v[48:49], v[56:57], v[56:57], v[48:49]
	s_nop 0
	v_pk_add_f32 v[48:49], v[48:49], v[50:51] op_sel_hi:[1,0]
	v_pk_mul_f32 v[50:51], v[12:13], v[126:127] op_sel_hi:[0,1]
	v_pk_fma_f32 v[52:53], v[34:35], v[8:9], v[50:51] op_sel_hi:[1,0,1] neg_lo:[0,0,1] neg_hi:[0,0,1]
	v_pk_mul_f32 v[34:35], v[12:13], v[124:125] op_sel_hi:[0,1]
	v_pk_fma_f32 v[54:55], v[32:33], v[8:9], v[34:35] op_sel_hi:[1,0,1] neg_lo:[0,0,1] neg_hi:[0,0,1]
	s_nop 0
	v_pk_fma_f32 v[32:33], v[54:55], v[54:55], v[48:49]
	v_mul_f32_e32 v34, v55, v55
	v_pk_add_f32 v[32:33], v[32:33], v[34:35] op_sel_hi:[1,0]
	v_mul_f32_e32 v34, v53, v53
	v_pk_fma_f32 v[32:33], v[52:53], v[52:53], v[32:33]
	s_nop 0
	v_pk_add_f32 v[32:33], v[32:33], v[34:35] op_sel_hi:[1,0]
	v_pk_mul_f32 v[34:35], v[12:13], v[122:123] op_sel_hi:[0,1]
	v_pk_fma_f32 v[48:49], v[38:39], v[8:9], v[34:35] op_sel_hi:[1,0,1] neg_lo:[0,0,1] neg_hi:[0,0,1]
	v_pk_mul_f32 v[34:35], v[12:13], v[120:121] op_sel_hi:[0,1]
	v_pk_fma_f32 v[50:51], v[36:37], v[8:9], v[34:35] op_sel_hi:[1,0,1] neg_lo:[0,0,1] neg_hi:[0,0,1]
	s_nop 0
	v_pk_fma_f32 v[32:33], v[50:51], v[50:51], v[32:33]
	v_mul_f32_e32 v34, v51, v51
	v_pk_add_f32 v[32:33], v[32:33], v[34:35] op_sel_hi:[1,0]
	v_mul_f32_e32 v34, v49, v49
	v_pk_fma_f32 v[32:33], v[48:49], v[48:49], v[32:33]
	s_nop 0
	v_pk_add_f32 v[32:33], v[32:33], v[34:35] op_sel_hi:[1,0]
	v_pk_mul_f32 v[34:35], v[12:13], v[118:119] op_sel_hi:[0,1]
	v_pk_fma_f32 v[42:43], v[42:43], v[8:9], v[34:35] op_sel_hi:[1,0,1] neg_lo:[0,0,1] neg_hi:[0,0,1]
	v_pk_mul_f32 v[34:35], v[12:13], v[116:117] op_sel_hi:[0,1]
; DI unsigned pk2(float lo, float hi) { fl2_t f = {lo, hi}; bf2_t b = __builtin_convertvector(f, bf2_t); return __builtin_bit_cast(unsigned, b); }
; DI float bflo(unsigned u) { return __uint_as_float(u << 16); }
; DI float bfhi(unsigned u) { return __uint_as_float(u & 0xffff0000u); }
; DI float silu_f(float z) { return z / (1.f + __expf(-z)); }
; DI void diff_item(const Params& P, char* lds, int layer, int pair, int qt, int& tab_head) {
;     ...
;         float ss = 0.f;
; #pragma unroll
;         for (int dt = 0; dt < 4; ++dt)
; #pragma unroll
;             for (int i = 0; i < 16; ++i) {
;                 float o = O[dt][i] * inv - lam * cmb[(qs * 128 + 32 * dt + (i & 3) + 8 * (i >> 2) + 4 * hh) * 32 + r];
;                 O[dt][i] = o; ss += o * o;
;             }
;         ss = xhalf_sum(ss);
;         const float rstd = rsqrtf(ss * (1.f / 128.f) + EPS) * (1.f - lam_init);
;         const float* gs = P.g_sub + layer * 128;
;         u16* orow = base + (size_t)qpos * PO;
; #pragma unroll
;         for (int dt = 0; dt < 4; ++dt)
; #pragma unroll
;             for (int g = 0; g < 4; ++g) {
;                 const int d = 32 * dt + 8 * g + 4 * hh;
;                 u32x2 zz = *(const u32x2*)(orow + OFF_Z + 1536 + head * 128 + d);
;                 f32x4 gg = *(const f32x4*)(gs + d);
;                 float y0 = O[dt][4 * g + 0] * rstd * gg.x * silu_f(bflo(zz.x)), y1 = O[dt][4 * g + 1] * rstd * gg.y * silu_f(bfhi(zz.x));
;                 float y2 = O[dt][4 * g + 2] * rstd * gg.z * silu_f(bflo(zz.y)), y3 = O[dt][4 * g + 3] * rstd * gg.w * silu_f(bfhi(zz.y));
;                 u32x2 o = {pk2(y0, y1), pk2(y2, y3)};
;                 *(u32x2*)(orow + OFF_CQ + head * 128 + d) = o;
	v_pk_fma_f32 v[40:41], v[40:41], v[8:9], v[34:35] op_sel_hi:[1,0,1] neg_lo:[0,0,1] neg_hi:[0,0,1]
	s_nop 0
	v_pk_fma_f32 v[32:33], v[40:41], v[40:41], v[32:33]
	v_mul_f32_e32 v34, v41, v41
	v_pk_add_f32 v[32:33], v[32:33], v[34:35] op_sel_hi:[1,0]
	v_mul_f32_e32 v34, v43, v43
	v_pk_fma_f32 v[32:33], v[42:43], v[42:43], v[32:33]
	s_nop 0
	v_pk_add_f32 v[32:33], v[32:33], v[34:35] op_sel_hi:[1,0]
	v_pk_mul_f32 v[34:35], v[12:13], v[114:115] op_sel_hi:[0,1]
	v_pk_fma_f32 v[36:37], v[46:47], v[8:9], v[34:35] op_sel_hi:[1,0,1] neg_lo:[0,0,1] neg_hi:[0,0,1]
	v_pk_mul_f32 v[34:35], v[12:13], v[112:113] op_sel_hi:[0,1]
	v_pk_fma_f32 v[38:39], v[44:45], v[8:9], v[34:35] op_sel_hi:[1,0,1] neg_lo:[0,0,1] neg_hi:[0,0,1]
	s_nop 0
	v_pk_fma_f32 v[32:33], v[38:39], v[38:39], v[32:33]
	v_mul_f32_e32 v34, v39, v39
	v_pk_add_f32 v[32:33], v[32:33], v[34:35] op_sel_hi:[1,0]
	v_mul_f32_e32 v34, v37, v37
	v_pk_fma_f32 v[32:33], v[36:37], v[36:37], v[32:33]
	s_nop 0
	v_pk_add_f32 v[44:45], v[32:33], v[34:35] op_sel_hi:[1,0]
	v_pk_mul_f32 v[32:33], v[12:13], v[110:111] op_sel_hi:[0,1]
	v_pk_fma_f32 v[32:33], v[18:19], v[8:9], v[32:33] op_sel_hi:[1,0,1] neg_lo:[0,0,1] neg_hi:[0,0,1]
	v_pk_mul_f32 v[18:19], v[12:13], v[106:107] op_sel_hi:[0,1]
	v_pk_fma_f32 v[34:35], v[16:17], v[8:9], v[18:19] op_sel_hi:[1,0,1] neg_lo:[0,0,1] neg_hi:[0,0,1]
	s_nop 0
	v_pk_fma_f32 v[16:17], v[34:35], v[34:35], v[44:45]
	v_mul_f32_e32 v18, v35, v35
	v_pk_add_f32 v[16:17], v[16:17], v[18:19] op_sel_hi:[1,0]
	v_mul_f32_e32 v18, v33, v33
	v_pk_fma_f32 v[16:17], v[32:33], v[32:33], v[16:17]
	s_nop 0
	v_pk_add_f32 v[16:17], v[16:17], v[18:19] op_sel_hi:[1,0]
	v_pk_mul_f32 v[18:19], v[12:13], v[104:105] op_sel_hi:[0,1]
	v_pk_fma_f32 v[22:23], v[22:23], v[8:9], v[18:19] op_sel_hi:[1,0,1] neg_lo:[0,0,1] neg_hi:[0,0,1]
	v_pk_mul_f32 v[18:19], v[12:13], v[102:103] op_sel_hi:[0,1]
	v_pk_fma_f32 v[20:21], v[20:21], v[8:9], v[18:19] op_sel_hi:[1,0,1] neg_lo:[0,0,1] neg_hi:[0,0,1]
	s_nop 0
	v_pk_fma_f32 v[16:17], v[20:21], v[20:21], v[16:17]
	v_mul_f32_e32 v18, v21, v21
	v_pk_add_f32 v[16:17], v[16:17], v[18:19] op_sel_hi:[1,0]
	v_mul_f32_e32 v18, v23, v23
	v_pk_fma_f32 v[16:17], v[22:23], v[22:23], v[16:17]
	s_nop 0
	v_pk_add_f32 v[44:45], v[16:17], v[18:19] op_sel_hi:[1,0]
	v_pk_mul_f32 v[18:19], v[12:13], v[96:97] op_sel_hi:[0,1]
	v_pk_mul_f32 v[16:17], v[12:13], v[98:99] op_sel_hi:[0,1]
	v_pk_fma_f32 v[18:19], v[24:25], v[8:9], v[18:19] op_sel_hi:[1,0,1] neg_lo:[0,0,1] neg_hi:[0,0,1]
	v_pk_fma_f32 v[16:17], v[26:27], v[8:9], v[16:17] op_sel_hi:[1,0,1] neg_lo:[0,0,1] neg_hi:[0,0,1]
	v_pk_fma_f32 v[24:25], v[18:19], v[18:19], v[44:45]
	v_mul_f32_e32 v26, v19, v19
	v_pk_add_f32 v[24:25], v[24:25], v[26:27] op_sel_hi:[1,0]
	v_mul_f32_e32 v26, v17, v17
	v_pk_fma_f32 v[24:25], v[16:17], v[16:17], v[24:25]
	v_pk_mul_f32 v[12:13], v[12:13], v[94:95] op_sel_hi:[0,1]
	v_pk_add_f32 v[24:25], v[24:25], v[26:27] op_sel_hi:[1,0]
	v_pk_fma_f32 v[12:13], v[28:29], v[8:9], v[12:13] op_sel_hi:[1,0,1] neg_lo:[0,0,1] neg_hi:[0,0,1]
	flat_load_dwordx2 v[26:27], v[14:15] offset:32
	v_pk_fma_f32 v[24:25], v[12:13], v[12:13], v[24:25]
	v_mul_f32_e32 v8, v13, v13
	v_pk_add_f32 v[24:25], v[24:25], v[8:9] op_sel_hi:[1,0]
	v_mul_f32_e32 v8, v11, v11
	v_pk_fma_f32 v[24:25], v[10:11], v[10:11], v[24:25]
	s_waitcnt vmcnt(0) lgkmcnt(0)
	v_lshlrev_b32_e32 v28, 16, v88
	v_pk_add_f32 v[24:25], v[24:25], v[8:9] op_sel_hi:[1,0]
	v_and_b32_e32 v29, 0xffff0000, v88
	v_mov_b32_e32 v8, v24
	s_nop 1
	v_permlane32_swap_b32_e32 v24, v8
	v_add_f32_e32 v8, v24, v8
	v_fmamk_f32 v8, v8, 0x3c000000, v175
	v_cmp_gt_f32_e64 s[0:1], s66, v8
	v_mul_f32_e32 v24, 0x4b800000, v8
	v_lshlrev_b32_e32 v47, 16, v89
	v_cndmask_b32_e64 v8, v8, v24, s[0:1]
	v_rsq_f32_e32 v24, v8
	v_div_fmas_f32 v8, v150, v149, v148
	v_div_fixup_f32 v108, v8, v108, v9
	v_lshl_add_u64 v[8:9], v[164:165], 0, v[0:1]
	v_lshl_add_u64 v[160:161], v[8:9], 0, v[0:1]
	v_mul_f32_e32 v0, 0x45800000, v24
	v_cndmask_b32_e64 v0, v24, v0, s[0:1]
	v_mul_f32_e32 v0, v192, v0
	v_pk_mul_f32 v[24:25], v[92:93], v[0:1] op_sel_hi:[1,0]
	v_and_b32_e32 v60, 0xffff0000, v89
	v_pk_mul_f32 v[2:3], v[2:3], v[24:25]
	v_pk_mul_f32 v[24:25], v[90:91], v[0:1] op_sel_hi:[1,0]
	v_pk_mul_f32 v[2:3], v[100:101], v[2:3]
	v_pk_mul_f32 v[4:5], v[4:5], v[24:25]
	v_cvt_pk_bf16_f32 v2, v2, v3
	v_pk_mul_f32 v[4:5], v[108:109], v[4:5]
	v_mul_f32_e32 v24, 0xbfb8aa3b, v28
	v_cvt_pk_bf16_f32 v3, v4, v5
	v_mov_b32_e32 v156, v2
	v_mov_b32_e32 v157, v3
	flat_load_dwordx4 v[2:5], v[6:7] offset:32
	v_mul_f32_e32 v25, 0xbfb8aa3b, v29
	v_exp_f32_e32 v24, v24
	v_exp_f32_e32 v25, v25
	v_pk_mul_f32 v[12:13], v[12:13], v[0:1] op_sel_hi:[1,0]
	v_pk_mul_f32 v[10:11], v[10:11], v[0:1] op_sel_hi:[1,0]
	v_pk_add_f32 v[24:25], v[24:25], 1.0 op_sel_hi:[1,0]
	s_nop 0
	v_div_scale_f32 v30, s[0:1], v25, v25, v29
	v_rcp_f32_e32 v31, v30
	s_nop 0
	v_fma_f32 v44, -v30, v31, 1.0
	v_fmac_f32_e32 v31, v44, v31
	v_div_scale_f32 v44, vcc, v29, v25, v29
	v_mul_f32_e32 v45, v44, v31
	v_fma_f32 v46, -v30, v45, v44
	v_fmac_f32_e32 v45, v46, v31
	v_fma_f32 v30, -v30, v45, v44
	v_div_scale_f32 v44, s[0:1], v24, v24, v28
	v_rcp_f32_e32 v46, v44
	v_div_fmas_f32 v30, v30, v31, v45
	v_div_fixup_f32 v25, v30, v25, v29
	v_mul_f32_e32 v30, 0xbfb8aa3b, v47
	v_mul_f32_e32 v31, 0xbfb8aa3b, v60
	v_fma_f32 v29, -v44, v46, 1.0
	v_exp_f32_e32 v30, v30
	v_exp_f32_e32 v31, v31
	v_fmac_f32_e32 v46, v29, v46
	v_div_scale_f32 v29, vcc, v28, v24, v28
	v_mul_f32_e32 v45, v29, v46
	v_fma_f32 v61, -v44, v45, v29
	v_fmac_f32_e32 v45, v61, v46
	v_pk_add_f32 v[30:31], v[30:31], 1.0 op_sel_hi:[1,0]
	v_fma_f32 v29, -v44, v45, v29
	v_div_scale_f32 v44, s[0:1], v31, v31, v60
	v_rcp_f32_e32 v61, v44
	v_div_fmas_f32 v29, v29, v46, v45
	v_div_fixup_f32 v24, v29, v24, v28
	v_fma_f32 v28, -v44, v61, 1.0
	v_fmac_f32_e32 v61, v28, v61
	v_div_scale_f32 v28, vcc, v60, v31, v60
	v_mul_f32_e32 v29, v28, v61
	v_fma_f32 v45, -v44, v29, v28
	v_fmac_f32_e32 v29, v45, v61
	v_fma_f32 v28, -v44, v29, v28
	v_div_scale_f32 v44, s[0:1], v30, v30, v47
	v_rcp_f32_e32 v45, v44
	v_div_fmas_f32 v28, v28, v61, v29
	v_div_fixup_f32 v29, v28, v31, v60
	v_and_b32_e32 v60, 0xffff0000, v27
	v_fma_f32 v28, -v44, v45, 1.0
	v_fmac_f32_e32 v45, v28, v45
	v_div_scale_f32 v28, vcc, v47, v30, v47
	v_mul_f32_e32 v31, v28, v45
	v_fma_f32 v46, -v44, v31, v28
	v_fmac_f32_e32 v31, v46, v45
	v_fma_f32 v28, -v44, v31, v28
	v_div_fmas_f32 v28, v28, v45, v31
	v_div_fixup_f32 v28, v28, v30, v47
	v_pk_mul_f32 v[30:31], v[86:87], v[0:1] op_sel_hi:[1,0]
	s_waitcnt vmcnt(0) lgkmcnt(0)
; DI unsigned pk2(float lo, float hi) { fl2_t f = {lo, hi}; bf2_t b = __builtin_convertvector(f, bf2_t); return __builtin_bit_cast(unsigned, b); }
; DI float bflo(unsigned u) { return __uint_as_float(u << 16); }
; DI float bfhi(unsigned u) { return __uint_as_float(u & 0xffff0000u); }
; DI float silu_f(float z) { return z / (1.f + __expf(-z)); }
; DI void diff_item(const Params& P, char* lds, int layer, int pair, int qt, int& tab_head) {
;     ...
;                 const int d = 32 * dt + 8 * g + 4 * hh;
;                 u32x2 zz = *(const u32x2*)(orow + OFF_Z + 1536 + head * 128 + d);
;                 f32x4 gg = *(const f32x4*)(gs + d);
;                 float y0 = O[dt][4 * g + 0] * rstd * gg.x * silu_f(bflo(zz.x)), y1 = O[dt][4 * g + 1] * rstd * gg.y * silu_f(bfhi(zz.x));
;                 float y2 = O[dt][4 * g + 2] * rstd * gg.z * silu_f(bflo(zz.y)), y3 = O[dt][4 * g + 3] * rstd * gg.w * silu_f(bfhi(zz.y));
;                 u32x2 o = {pk2(y0, y1), pk2(y2, y3)};
;                 *(u32x2*)(orow + OFF_CQ + head * 128 + d) = o;
	v_pk_mul_f32 v[2:3], v[2:3], v[30:31]
	s_nop 0
	v_pk_mul_f32 v[2:3], v[24:25], v[2:3]
	v_pk_mul_f32 v[24:25], v[84:85], v[0:1] op_sel_hi:[1,0]
	v_cvt_pk_bf16_f32 v2, v2, v3
	v_pk_mul_f32 v[4:5], v[4:5], v[24:25]
	v_lshlrev_b32_e32 v30, 16, v26
	v_pk_mul_f32 v[4:5], v[28:29], v[4:5]
	v_and_b32_e32 v26, 0xffff0000, v26
	v_cvt_pk_bf16_f32 v3, v4, v5
	v_mov_b32_e32 v158, v2
	v_mov_b32_e32 v159, v3
	s_nop 1
	v_permlane32_swap_b32_e32 v156, v158
	v_permlane32_swap_b32_e32 v157, v159
	s_nop 1
	global_store_dwordx4 v[160:161], v[156:159], off
	flat_load_dwordx4 v[2:5], v[6:7] offset:64
	v_mul_f32_e32 v24, 0xbfb8aa3b, v30
	v_mul_f32_e32 v25, 0xbfb8aa3b, v26
	v_exp_f32_e32 v24, v24
	v_exp_f32_e32 v25, v25
	flat_load_dwordx2 v[28:29], v[14:15] offset:48
	v_pk_add_f32 v[24:25], v[24:25], 1.0 op_sel_hi:[1,0]
	s_nop 0
	v_div_scale_f32 v31, s[0:1], v25, v25, v26
	v_rcp_f32_e32 v44, v31
	s_nop 0
	v_fma_f32 v45, -v31, v44, 1.0
	v_fmac_f32_e32 v44, v45, v44
	v_div_scale_f32 v45, vcc, v26, v25, v26
	v_mul_f32_e32 v46, v45, v44
	v_fma_f32 v47, -v31, v46, v45
	v_fmac_f32_e32 v46, v47, v44
	v_fma_f32 v31, -v31, v46, v45
	v_div_scale_f32 v45, s[0:1], v24, v24, v30
	v_rcp_f32_e32 v47, v45
	v_div_fmas_f32 v31, v31, v44, v46
	v_div_fixup_f32 v25, v31, v25, v26
	v_lshlrev_b32_e32 v46, 16, v27
	v_fma_f32 v26, -v45, v47, 1.0
	v_fmac_f32_e32 v47, v26, v47
	v_mul_f32_e32 v26, 0xbfb8aa3b, v46
	v_mul_f32_e32 v27, 0xbfb8aa3b, v60
	v_exp_f32_e32 v26, v26
	v_exp_f32_e32 v27, v27
	v_div_scale_f32 v31, vcc, v30, v24, v30
	v_mul_f32_e32 v44, v31, v47
	v_fma_f32 v61, -v45, v44, v31
	v_fmac_f32_e32 v44, v61, v47
	v_pk_add_f32 v[26:27], v[26:27], 1.0 op_sel_hi:[1,0]
	v_fma_f32 v31, -v45, v44, v31
	v_div_scale_f32 v45, s[0:1], v27, v27, v60
	v_rcp_f32_e32 v61, v45
	v_div_fmas_f32 v31, v31, v47, v44
	v_div_fixup_f32 v24, v31, v24, v30
	v_fma_f32 v30, -v45, v61, 1.0
	v_fmac_f32_e32 v61, v30, v61
	v_div_scale_f32 v30, vcc, v60, v27, v60
	v_mul_f32_e32 v31, v30, v61
	v_fma_f32 v44, -v45, v31, v30
	v_fmac_f32_e32 v31, v44, v61
	v_div_scale_f32 v44, s[0:1], v26, v26, v46
	v_fma_f32 v30, -v45, v31, v30
	v_rcp_f32_e32 v45, v44
	v_div_fmas_f32 v30, v30, v61, v31
	v_div_fixup_f32 v27, v30, v27, v60
	v_fma_f32 v30, -v44, v45, 1.0
	v_fmac_f32_e32 v45, v30, v45
	v_div_scale_f32 v30, vcc, v46, v26, v46
	v_mul_f32_e32 v31, v30, v45
	v_fma_f32 v47, -v44, v31, v30
	v_fmac_f32_e32 v31, v47, v45
	v_fma_f32 v30, -v44, v31, v30
	v_div_fmas_f32 v30, v30, v45, v31
	v_div_fixup_f32 v26, v30, v26, v46
	v_pk_mul_f32 v[30:31], v[82:83], v[0:1] op_sel_hi:[1,0]
	s_waitcnt vmcnt(0) lgkmcnt(0)
	v_pk_mul_f32 v[2:3], v[2:3], v[30:31]
	s_nop 0
	v_pk_mul_f32 v[2:3], v[2:3], v[24:25]
	v_pk_mul_f32 v[24:25], v[80:81], v[0:1] op_sel_hi:[1,0]
	v_cvt_pk_bf16_f32 v2, v2, v3
	v_pk_mul_f32 v[4:5], v[4:5], v[24:25]
	flat_load_dwordx2 v[30:31], v[14:15] offset:64
	v_pk_mul_f32 v[4:5], v[4:5], v[26:27]
	v_lshlrev_b32_e32 v44, 16, v28
	v_cvt_pk_bf16_f32 v3, v4, v5
	v_mov_b32_e32 v156, v2
	v_mov_b32_e32 v157, v3
	flat_load_dwordx4 v[2:5], v[6:7] offset:96
	v_and_b32_e32 v26, 0xffff0000, v28
	v_mul_f32_e32 v24, 0xbfb8aa3b, v44
	v_mul_f32_e32 v25, 0xbfb8aa3b, v26
	v_exp_f32_e32 v24, v24
	v_exp_f32_e32 v25, v25
	v_lshlrev_b32_e32 v60, 16, v29
	v_and_b32_e32 v29, 0xffff0000, v29
	v_pk_add_f32 v[24:25], v[24:25], 1.0 op_sel_hi:[1,0]
	s_nop 0
	v_div_scale_f32 v27, s[0:1], v25, v25, v26
	v_rcp_f32_e32 v28, v27
	s_nop 0
	v_fma_f32 v45, -v27, v28, 1.0
	v_fmac_f32_e32 v28, v45, v28
	v_div_scale_f32 v45, vcc, v26, v25, v26
	v_mul_f32_e32 v46, v45, v28
	v_fma_f32 v47, -v27, v46, v45
	v_fmac_f32_e32 v46, v47, v28
	v_fma_f32 v27, -v27, v46, v45
	v_div_scale_f32 v45, s[0:1], v24, v24, v44
	v_rcp_f32_e32 v47, v45
	v_div_fmas_f32 v27, v27, v28, v46
	v_div_fixup_f32 v25, v27, v25, v26
	v_mul_f32_e32 v27, 0xbfb8aa3b, v29
	v_fma_f32 v26, -v45, v47, 1.0
	v_fmac_f32_e32 v47, v26, v47
	v_mul_f32_e32 v26, 0xbfb8aa3b, v60
	v_exp_f32_e32 v26, v26
	v_exp_f32_e32 v27, v27
	v_div_scale_f32 v28, vcc, v44, v24, v44
	v_mul_f32_e32 v46, v28, v47
	v_fma_f32 v61, -v45, v46, v28
	v_fmac_f32_e32 v46, v61, v47
	v_pk_add_f32 v[26:27], v[26:27], 1.0 op_sel_hi:[1,0]
	v_fma_f32 v28, -v45, v46, v28
	v_div_scale_f32 v45, s[0:1], v27, v27, v29
	v_rcp_f32_e32 v61, v45
	v_div_fmas_f32 v28, v28, v47, v46
	v_div_fixup_f32 v24, v28, v24, v44
	v_fma_f32 v28, -v45, v61, 1.0
	v_fmac_f32_e32 v61, v28, v61
	v_div_scale_f32 v28, vcc, v29, v27, v29
	v_mul_f32_e32 v44, v28, v61
	v_fma_f32 v46, -v45, v44, v28
	v_fmac_f32_e32 v44, v46, v61
	v_fma_f32 v28, -v45, v44, v28
	v_div_scale_f32 v45, s[0:1], v26, v26, v60
	v_rcp_f32_e32 v46, v45
	v_div_fmas_f32 v28, v28, v61, v44
	v_div_fixup_f32 v27, v28, v27, v29
	v_fma_f32 v28, -v45, v46, 1.0
	v_fmac_f32_e32 v46, v28, v46
	v_div_scale_f32 v28, vcc, v60, v26, v60
	v_mul_f32_e32 v29, v28, v46
	v_fma_f32 v44, -v45, v29, v28
	v_fmac_f32_e32 v29, v44, v46
	v_fma_f32 v28, -v45, v29, v28
	v_div_fmas_f32 v28, v28, v46, v29
	v_div_fixup_f32 v26, v28, v26, v60
	v_pk_mul_f32 v[28:29], v[76:77], v[0:1] op_sel_hi:[1,0]
	s_waitcnt vmcnt(0) lgkmcnt(0)
; DI unsigned pk2(float lo, float hi) { fl2_t f = {lo, hi}; bf2_t b = __builtin_convertvector(f, bf2_t); return __builtin_bit_cast(unsigned, b); }
; DI float bflo(unsigned u) { return __uint_as_float(u << 16); }
; DI float bfhi(unsigned u) { return __uint_as_float(u & 0xffff0000u); }
; DI float silu_f(float z) { return z / (1.f + __expf(-z)); }
; DI void diff_item(const Params& P, char* lds, int layer, int pair, int qt, int& tab_head) {
;     ...
;                 const int d = 32 * dt + 8 * g + 4 * hh;
;                 u32x2 zz = *(const u32x2*)(orow + OFF_Z + 1536 + head * 128 + d);
;                 f32x4 gg = *(const f32x4*)(gs + d);
;                 float y0 = O[dt][4 * g + 0] * rstd * gg.x * silu_f(bflo(zz.x)), y1 = O[dt][4 * g + 1] * rstd * gg.y * silu_f(bfhi(zz.x));
;                 float y2 = O[dt][4 * g + 2] * rstd * gg.z * silu_f(bflo(zz.y)), y3 = O[dt][4 * g + 3] * rstd * gg.w * silu_f(bfhi(zz.y));
;                 u32x2 o = {pk2(y0, y1), pk2(y2, y3)};
;                 *(u32x2*)(orow + OFF_CQ + head * 128 + d) = o;
	v_lshlrev_b32_e32 v44, 16, v30
	v_lshlrev_b32_e32 v60, 16, v31
	v_and_b32_e32 v31, 0xffff0000, v31
	v_pk_mul_f32 v[2:3], v[28:29], v[2:3]
	s_nop 0
	v_pk_mul_f32 v[2:3], v[2:3], v[24:25]
	v_pk_mul_f32 v[24:25], v[78:79], v[0:1] op_sel_hi:[1,0]
	v_cvt_pk_bf16_f32 v2, v2, v3
	v_pk_mul_f32 v[4:5], v[24:25], v[4:5]
	v_and_b32_e32 v28, 0xffff0000, v30
	v_pk_mul_f32 v[4:5], v[4:5], v[26:27]
	v_mul_f32_e32 v24, 0xbfb8aa3b, v44
	v_cvt_pk_bf16_f32 v3, v4, v5
	v_mov_b32_e32 v158, v2
	v_mov_b32_e32 v159, v3
	s_nop 1
	v_permlane32_swap_b32_e32 v156, v158
	v_permlane32_swap_b32_e32 v157, v159
	s_nop 1
	global_store_dwordx4 v[160:161], v[156:159], off offset:32
	flat_load_dwordx4 v[2:5], v[6:7] offset:128
	v_mul_f32_e32 v25, 0xbfb8aa3b, v28
	v_exp_f32_e32 v24, v24
	v_exp_f32_e32 v25, v25
	flat_load_dwordx2 v[26:27], v[14:15] offset:80
	v_pk_add_f32 v[24:25], v[24:25], 1.0 op_sel_hi:[1,0]
	s_nop 0
	v_div_scale_f32 v29, s[0:1], v25, v25, v28
	v_rcp_f32_e32 v30, v29
	s_nop 0
	v_fma_f32 v45, -v29, v30, 1.0
	v_fmac_f32_e32 v30, v45, v30
	v_div_scale_f32 v45, vcc, v28, v25, v28
	v_mul_f32_e32 v46, v45, v30
	v_fma_f32 v47, -v29, v46, v45
	v_fmac_f32_e32 v46, v47, v30
	v_fma_f32 v29, -v29, v46, v45
	v_div_scale_f32 v45, s[0:1], v24, v24, v44
	v_rcp_f32_e32 v47, v45
	v_div_fmas_f32 v29, v29, v30, v46
	v_div_fixup_f32 v25, v29, v25, v28
	v_mul_f32_e32 v29, 0xbfb8aa3b, v31
	v_fma_f32 v28, -v45, v47, 1.0
	v_fmac_f32_e32 v47, v28, v47
	v_mul_f32_e32 v28, 0xbfb8aa3b, v60
	v_exp_f32_e32 v28, v28
	v_exp_f32_e32 v29, v29
	v_div_scale_f32 v30, vcc, v44, v24, v44
	v_mul_f32_e32 v46, v30, v47
	v_fma_f32 v61, -v45, v46, v30
	v_fmac_f32_e32 v46, v61, v47
	v_pk_add_f32 v[28:29], v[28:29], 1.0 op_sel_hi:[1,0]
	v_fma_f32 v30, -v45, v46, v30
	v_div_scale_f32 v45, s[0:1], v29, v29, v31
	v_rcp_f32_e32 v61, v45
	v_div_fmas_f32 v30, v30, v47, v46
	v_div_fixup_f32 v24, v30, v24, v44
	v_fma_f32 v30, -v45, v61, 1.0
	v_fmac_f32_e32 v61, v30, v61
	v_div_scale_f32 v30, vcc, v31, v29, v31
	v_mul_f32_e32 v44, v30, v61
	v_fma_f32 v46, -v45, v44, v30
	v_fmac_f32_e32 v44, v46, v61
	v_fma_f32 v30, -v45, v44, v30
	v_div_scale_f32 v45, s[0:1], v28, v28, v60
	v_rcp_f32_e32 v46, v45
	v_div_fmas_f32 v30, v30, v61, v44
	v_div_fixup_f32 v29, v30, v29, v31
	v_fma_f32 v30, -v45, v46, 1.0
	v_fmac_f32_e32 v46, v30, v46
	v_div_scale_f32 v30, vcc, v60, v28, v60
	v_mul_f32_e32 v31, v30, v46
	v_fma_f32 v44, -v45, v31, v30
	v_fmac_f32_e32 v31, v44, v46
	v_fma_f32 v30, -v45, v31, v30
	v_div_fmas_f32 v30, v30, v46, v31
	v_div_fixup_f32 v28, v30, v28, v60
	v_pk_mul_f32 v[30:31], v[74:75], v[0:1] op_sel_hi:[1,0]
	s_waitcnt vmcnt(0) lgkmcnt(0)
	v_and_b32_e32 v60, 0xffff0000, v27
	v_pk_mul_f32 v[2:3], v[30:31], v[2:3]
	v_lshlrev_b32_e32 v30, 16, v26
	v_pk_mul_f32 v[2:3], v[2:3], v[24:25]
	v_pk_mul_f32 v[24:25], v[72:73], v[0:1] op_sel_hi:[1,0]
	v_cvt_pk_bf16_f32 v2, v2, v3
	v_pk_mul_f32 v[4:5], v[24:25], v[4:5]
	v_and_b32_e32 v26, 0xffff0000, v26
	v_pk_mul_f32 v[4:5], v[4:5], v[28:29]
	v_mul_f32_e32 v24, 0xbfb8aa3b, v30
	v_cvt_pk_bf16_f32 v3, v4, v5
	v_mov_b32_e32 v156, v2
	v_mov_b32_e32 v157, v3
	flat_load_dwordx4 v[2:5], v[6:7] offset:160
	v_exp_f32_e32 v28, v24
	v_mul_f32_e32 v24, 0xbfb8aa3b, v26
	v_exp_f32_e32 v29, v24
	flat_load_dwordx2 v[24:25], v[14:15] offset:96
	v_pk_add_f32 v[28:29], v[28:29], 1.0 op_sel_hi:[1,0]
	s_nop 0
	v_div_scale_f32 v31, s[0:1], v29, v29, v26
	v_rcp_f32_e32 v44, v31
	s_nop 0
	v_fma_f32 v45, -v31, v44, 1.0
	v_fmac_f32_e32 v44, v45, v44
	v_div_scale_f32 v45, vcc, v26, v29, v26
	v_mul_f32_e32 v46, v45, v44
	v_fma_f32 v47, -v31, v46, v45
	v_fmac_f32_e32 v46, v47, v44
	v_fma_f32 v31, -v31, v46, v45
	v_div_scale_f32 v45, s[0:1], v28, v28, v30
	v_rcp_f32_e32 v47, v45
	v_div_fmas_f32 v31, v31, v44, v46
	v_div_fixup_f32 v29, v31, v29, v26
	v_lshlrev_b32_e32 v46, 16, v27
	v_fma_f32 v26, -v45, v47, 1.0
	v_fmac_f32_e32 v47, v26, v47
	v_mul_f32_e32 v26, 0xbfb8aa3b, v46
	v_mul_f32_e32 v27, 0xbfb8aa3b, v60
	v_exp_f32_e32 v26, v26
	v_exp_f32_e32 v27, v27
	v_div_scale_f32 v31, vcc, v30, v28, v30
	v_mul_f32_e32 v44, v31, v47
	v_fma_f32 v61, -v45, v44, v31
	v_fmac_f32_e32 v44, v61, v47
	v_pk_add_f32 v[26:27], v[26:27], 1.0 op_sel_hi:[1,0]
	v_fma_f32 v31, -v45, v44, v31
	v_div_scale_f32 v45, s[0:1], v27, v27, v60
	v_rcp_f32_e32 v61, v45
	v_div_fmas_f32 v31, v31, v47, v44
	v_div_fixup_f32 v28, v31, v28, v30
	v_fma_f32 v30, -v45, v61, 1.0
	v_fmac_f32_e32 v61, v30, v61
	v_div_scale_f32 v30, vcc, v60, v27, v60
	v_mul_f32_e32 v31, v30, v61
	v_fma_f32 v44, -v45, v31, v30
	v_fmac_f32_e32 v31, v44, v61
	v_div_scale_f32 v44, s[0:1], v26, v26, v46
	v_fma_f32 v30, -v45, v31, v30
	v_rcp_f32_e32 v45, v44
	v_div_fmas_f32 v30, v30, v61, v31
	v_div_fixup_f32 v27, v30, v27, v60
	v_fma_f32 v30, -v44, v45, 1.0
	v_fmac_f32_e32 v45, v30, v45
	v_div_scale_f32 v30, vcc, v46, v26, v46
	v_mul_f32_e32 v31, v30, v45
	v_fma_f32 v47, -v44, v31, v30
	v_fmac_f32_e32 v31, v47, v45
	v_fma_f32 v30, -v44, v31, v30
	v_div_fmas_f32 v30, v30, v45, v31
	v_div_fixup_f32 v26, v30, v26, v46
	v_pk_mul_f32 v[30:31], v[70:71], v[0:1] op_sel_hi:[1,0]
	s_waitcnt vmcnt(0) lgkmcnt(0)
; DI unsigned pk2(float lo, float hi) { fl2_t f = {lo, hi}; bf2_t b = __builtin_convertvector(f, bf2_t); return __builtin_bit_cast(unsigned, b); }
; DI float bflo(unsigned u) { return __uint_as_float(u << 16); }
; DI float bfhi(unsigned u) { return __uint_as_float(u & 0xffff0000u); }
; DI float silu_f(float z) { return z / (1.f + __expf(-z)); }
; DI void diff_item(const Params& P, char* lds, int layer, int pair, int qt, int& tab_head) {
;     ...
;                 const int d = 32 * dt + 8 * g + 4 * hh;
;                 u32x2 zz = *(const u32x2*)(orow + OFF_Z + 1536 + head * 128 + d);
;                 f32x4 gg = *(const f32x4*)(gs + d);
;                 float y0 = O[dt][4 * g + 0] * rstd * gg.x * silu_f(bflo(zz.x)), y1 = O[dt][4 * g + 1] * rstd * gg.y * silu_f(bfhi(zz.x));
;                 float y2 = O[dt][4 * g + 2] * rstd * gg.z * silu_f(bflo(zz.y)), y3 = O[dt][4 * g + 3] * rstd * gg.w * silu_f(bfhi(zz.y));
;                 u32x2 o = {pk2(y0, y1), pk2(y2, y3)};
;                 *(u32x2*)(orow + OFF_CQ + head * 128 + d) = o;
	v_pk_mul_f32 v[2:3], v[30:31], v[2:3]
	s_nop 0
	v_pk_mul_f32 v[2:3], v[2:3], v[28:29]
	v_pk_mul_f32 v[28:29], v[68:69], v[0:1] op_sel_hi:[1,0]
	v_cvt_pk_bf16_f32 v2, v2, v3
	v_pk_mul_f32 v[4:5], v[28:29], v[4:5]
	flat_load_dwordx2 v[28:29], v[14:15] offset:112
	v_pk_mul_f32 v[4:5], v[4:5], v[26:27]
	v_lshlrev_b32_e32 v30, 16, v24
	v_cvt_pk_bf16_f32 v3, v4, v5
	v_mov_b32_e32 v158, v2
	v_mov_b32_e32 v159, v3
	s_nop 1
	v_permlane32_swap_b32_e32 v156, v158
	v_permlane32_swap_b32_e32 v157, v159
	s_nop 1
	global_store_dwordx4 v[160:161], v[156:159], off offset:64
	flat_load_dwordx4 v[2:5], v[6:7] offset:192
	v_and_b32_e32 v24, 0xffff0000, v24
	v_mul_f32_e32 v26, 0xbfb8aa3b, v30
	v_mul_f32_e32 v27, 0xbfb8aa3b, v24
	v_exp_f32_e32 v26, v26
	v_exp_f32_e32 v27, v27
	v_and_b32_e32 v60, 0xffff0000, v25
	v_pk_add_f32 v[26:27], v[26:27], 1.0 op_sel_hi:[1,0]
	s_nop 0
	v_div_scale_f32 v31, s[0:1], v27, v27, v24
	v_rcp_f32_e32 v44, v31
	s_nop 0
	v_fma_f32 v45, -v31, v44, 1.0
	v_fmac_f32_e32 v44, v45, v44
	v_div_scale_f32 v45, vcc, v24, v27, v24
	v_mul_f32_e32 v46, v45, v44
	v_fma_f32 v47, -v31, v46, v45
	v_fmac_f32_e32 v46, v47, v44
	v_fma_f32 v31, -v31, v46, v45
	v_div_scale_f32 v45, s[0:1], v26, v26, v30
	v_rcp_f32_e32 v47, v45
	v_div_fmas_f32 v31, v31, v44, v46
	v_div_fixup_f32 v27, v31, v27, v24
	v_lshlrev_b32_e32 v46, 16, v25
	v_fma_f32 v24, -v45, v47, 1.0
	v_fmac_f32_e32 v47, v24, v47
	v_mul_f32_e32 v24, 0xbfb8aa3b, v46
	v_mul_f32_e32 v25, 0xbfb8aa3b, v60
	v_exp_f32_e32 v24, v24
	v_exp_f32_e32 v25, v25
	v_div_scale_f32 v31, vcc, v30, v26, v30
	v_mul_f32_e32 v44, v31, v47
	v_fma_f32 v61, -v45, v44, v31
	v_fmac_f32_e32 v44, v61, v47
	v_pk_add_f32 v[24:25], v[24:25], 1.0 op_sel_hi:[1,0]
	v_fma_f32 v31, -v45, v44, v31
	v_div_scale_f32 v45, s[0:1], v25, v25, v60
	v_rcp_f32_e32 v61, v45
	v_div_fmas_f32 v31, v31, v47, v44
	v_div_fixup_f32 v26, v31, v26, v30
	v_fma_f32 v30, -v45, v61, 1.0
	v_fmac_f32_e32 v61, v30, v61
	v_div_scale_f32 v30, vcc, v60, v25, v60
	v_mul_f32_e32 v31, v30, v61
	v_fma_f32 v44, -v45, v31, v30
	v_fmac_f32_e32 v31, v44, v61
	v_div_scale_f32 v44, s[0:1], v24, v24, v46
	v_fma_f32 v30, -v45, v31, v30
	v_rcp_f32_e32 v45, v44
	v_div_fmas_f32 v30, v30, v61, v31
	v_div_fixup_f32 v25, v30, v25, v60
	v_fma_f32 v30, -v44, v45, 1.0
	v_fmac_f32_e32 v45, v30, v45
	v_div_scale_f32 v30, vcc, v46, v24, v46
	v_mul_f32_e32 v31, v30, v45
	v_fma_f32 v47, -v44, v31, v30
	v_fmac_f32_e32 v31, v47, v45
	v_fma_f32 v30, -v44, v31, v30
	v_div_fmas_f32 v30, v30, v45, v31
	v_div_fixup_f32 v24, v30, v24, v46
	v_pk_mul_f32 v[30:31], v[66:67], v[0:1] op_sel_hi:[1,0]
	s_waitcnt vmcnt(0) lgkmcnt(0)
	v_and_b32_e32 v60, 0xffff0000, v29
	v_pk_mul_f32 v[2:3], v[30:31], v[2:3]
	s_nop 0
	v_pk_mul_f32 v[2:3], v[2:3], v[26:27]
	v_pk_mul_f32 v[26:27], v[64:65], v[0:1] op_sel_hi:[1,0]
	v_cvt_pk_bf16_f32 v2, v2, v3
	v_pk_mul_f32 v[4:5], v[26:27], v[4:5]
	v_lshlrev_b32_e32 v30, 16, v28
	v_pk_mul_f32 v[4:5], v[4:5], v[24:25]
	v_and_b32_e32 v28, 0xffff0000, v28
	v_cvt_pk_bf16_f32 v3, v4, v5
	v_mov_b32_e32 v156, v2
	v_mov_b32_e32 v157, v3
	flat_load_dwordx4 v[2:5], v[6:7] offset:224
	v_mul_f32_e32 v24, 0xbfb8aa3b, v30
	v_mul_f32_e32 v25, 0xbfb8aa3b, v28
	v_exp_f32_e32 v24, v24
	v_exp_f32_e32 v25, v25
	flat_load_dwordx2 v[26:27], v[14:15] offset:128
	v_pk_add_f32 v[24:25], v[24:25], 1.0 op_sel_hi:[1,0]
	s_nop 0
	v_div_scale_f32 v31, s[0:1], v25, v25, v28
	v_rcp_f32_e32 v44, v31
	s_nop 0
	v_fma_f32 v45, -v31, v44, 1.0
	v_fmac_f32_e32 v44, v45, v44
	v_div_scale_f32 v45, vcc, v28, v25, v28
	v_mul_f32_e32 v46, v45, v44
	v_fma_f32 v47, -v31, v46, v45
	v_fmac_f32_e32 v46, v47, v44
	v_fma_f32 v31, -v31, v46, v45
	v_div_scale_f32 v45, s[0:1], v24, v24, v30
	v_rcp_f32_e32 v47, v45
	v_div_fmas_f32 v31, v31, v44, v46
	v_div_fixup_f32 v25, v31, v25, v28
	v_lshlrev_b32_e32 v46, 16, v29
	v_fma_f32 v28, -v45, v47, 1.0
	v_fmac_f32_e32 v47, v28, v47
	v_mul_f32_e32 v28, 0xbfb8aa3b, v46
	v_mul_f32_e32 v29, 0xbfb8aa3b, v60
	v_exp_f32_e32 v28, v28
	v_exp_f32_e32 v29, v29
	v_div_scale_f32 v31, vcc, v30, v24, v30
	v_mul_f32_e32 v44, v31, v47
	v_fma_f32 v61, -v45, v44, v31
	v_fmac_f32_e32 v44, v61, v47
	v_pk_add_f32 v[28:29], v[28:29], 1.0 op_sel_hi:[1,0]
	v_fma_f32 v31, -v45, v44, v31
	v_div_scale_f32 v45, s[0:1], v29, v29, v60
	v_rcp_f32_e32 v61, v45
	v_div_fmas_f32 v31, v31, v47, v44
	v_div_fixup_f32 v24, v31, v24, v30
	v_fma_f32 v30, -v45, v61, 1.0
	v_fmac_f32_e32 v61, v30, v61
	v_div_scale_f32 v30, vcc, v60, v29, v60
	v_mul_f32_e32 v31, v30, v61
	v_fma_f32 v44, -v45, v31, v30
	v_fmac_f32_e32 v31, v44, v61
	v_div_scale_f32 v44, s[0:1], v28, v28, v46
	v_fma_f32 v30, -v45, v31, v30
	v_rcp_f32_e32 v45, v44
	v_div_fmas_f32 v30, v30, v61, v31
	v_div_fixup_f32 v29, v30, v29, v60
	v_fma_f32 v30, -v44, v45, 1.0
	v_fmac_f32_e32 v45, v30, v45
	v_div_scale_f32 v30, vcc, v46, v28, v46
	v_mul_f32_e32 v31, v30, v45
	v_fma_f32 v47, -v44, v31, v30
	v_fmac_f32_e32 v31, v47, v45
	v_fma_f32 v30, -v44, v31, v30
	v_div_fmas_f32 v30, v30, v45, v31
	v_div_fixup_f32 v28, v30, v28, v46
	v_pk_mul_f32 v[30:31], v[58:59], v[0:1] op_sel_hi:[1,0]
	s_waitcnt vmcnt(0) lgkmcnt(0)
; DI unsigned pk2(float lo, float hi) { fl2_t f = {lo, hi}; bf2_t b = __builtin_convertvector(f, bf2_t); return __builtin_bit_cast(unsigned, b); }
; DI float bflo(unsigned u) { return __uint_as_float(u << 16); }
; DI float bfhi(unsigned u) { return __uint_as_float(u & 0xffff0000u); }
; DI float silu_f(float z) { return z / (1.f + __expf(-z)); }
; DI void diff_item(const Params& P, char* lds, int layer, int pair, int qt, int& tab_head) {
;     ...
;                 const int d = 32 * dt + 8 * g + 4 * hh;
;                 u32x2 zz = *(const u32x2*)(orow + OFF_Z + 1536 + head * 128 + d);
;                 f32x4 gg = *(const f32x4*)(gs + d);
;                 float y0 = O[dt][4 * g + 0] * rstd * gg.x * silu_f(bflo(zz.x)), y1 = O[dt][4 * g + 1] * rstd * gg.y * silu_f(bfhi(zz.x));
;                 float y2 = O[dt][4 * g + 2] * rstd * gg.z * silu_f(bflo(zz.y)), y3 = O[dt][4 * g + 3] * rstd * gg.w * silu_f(bfhi(zz.y));
;                 u32x2 o = {pk2(y0, y1), pk2(y2, y3)};
;                 *(u32x2*)(orow + OFF_CQ + head * 128 + d) = o;
	v_pk_mul_f32 v[2:3], v[30:31], v[2:3]
	s_nop 0
	v_pk_mul_f32 v[2:3], v[2:3], v[24:25]
	v_pk_mul_f32 v[24:25], v[56:57], v[0:1] op_sel_hi:[1,0]
	v_cvt_pk_bf16_f32 v2, v2, v3
	v_pk_mul_f32 v[4:5], v[24:25], v[4:5]
	s_nop 0
	v_pk_mul_f32 v[4:5], v[4:5], v[28:29]
	flat_load_dwordx2 v[28:29], v[14:15] offset:144
	v_cvt_pk_bf16_f32 v3, v4, v5
	v_mov_b32_e32 v158, v2
	v_mov_b32_e32 v159, v3
	s_nop 1
	v_permlane32_swap_b32_e32 v156, v158
	v_permlane32_swap_b32_e32 v157, v159
	s_nop 1
	global_store_dwordx4 v[160:161], v[156:159], off offset:96
	flat_load_dwordx4 v[2:5], v[6:7] offset:256
	v_lshlrev_b32_e32 v30, 16, v26
	v_and_b32_e32 v26, 0xffff0000, v26
	v_mul_f32_e32 v24, 0xbfb8aa3b, v30
	v_mul_f32_e32 v25, 0xbfb8aa3b, v26
	v_exp_f32_e32 v24, v24
	v_exp_f32_e32 v25, v25
	v_and_b32_e32 v56, 0xffff0000, v27
	v_pk_add_f32 v[24:25], v[24:25], 1.0 op_sel_hi:[1,0]
	s_nop 0
	v_div_scale_f32 v31, s[0:1], v25, v25, v26
	v_rcp_f32_e32 v44, v31
	s_nop 0
	v_fma_f32 v45, -v31, v44, 1.0
	v_fmac_f32_e32 v44, v45, v44
	v_div_scale_f32 v45, vcc, v26, v25, v26
	v_mul_f32_e32 v46, v45, v44
	v_fma_f32 v47, -v31, v46, v45
	v_fmac_f32_e32 v46, v47, v44
	v_fma_f32 v31, -v31, v46, v45
	v_div_scale_f32 v45, s[0:1], v24, v24, v30
	v_rcp_f32_e32 v47, v45
	v_div_fmas_f32 v31, v31, v44, v46
	v_div_fixup_f32 v25, v31, v25, v26
	v_lshlrev_b32_e32 v46, 16, v27
	v_fma_f32 v26, -v45, v47, 1.0
	v_fmac_f32_e32 v47, v26, v47
	v_mul_f32_e32 v26, 0xbfb8aa3b, v46
	v_mul_f32_e32 v27, 0xbfb8aa3b, v56
	v_exp_f32_e32 v26, v26
	v_exp_f32_e32 v27, v27
	v_div_scale_f32 v31, vcc, v30, v24, v30
	v_mul_f32_e32 v44, v31, v47
	v_fma_f32 v57, -v45, v44, v31
	v_fmac_f32_e32 v44, v57, v47
	v_pk_add_f32 v[26:27], v[26:27], 1.0 op_sel_hi:[1,0]
	v_fma_f32 v31, -v45, v44, v31
	v_div_scale_f32 v45, s[0:1], v27, v27, v56
	v_rcp_f32_e32 v57, v45
	v_div_fmas_f32 v31, v31, v47, v44
	v_div_fixup_f32 v24, v31, v24, v30
	v_fma_f32 v30, -v45, v57, 1.0
	v_fmac_f32_e32 v57, v30, v57
	v_div_scale_f32 v30, vcc, v56, v27, v56
	v_mul_f32_e32 v31, v30, v57
	v_fma_f32 v44, -v45, v31, v30
	v_fmac_f32_e32 v31, v44, v57
	v_div_scale_f32 v44, s[0:1], v26, v26, v46
	v_fma_f32 v30, -v45, v31, v30
	v_rcp_f32_e32 v45, v44
	v_div_fmas_f32 v30, v30, v57, v31
	v_div_fixup_f32 v27, v30, v27, v56
	v_fma_f32 v30, -v44, v45, 1.0
	v_fmac_f32_e32 v45, v30, v45
	v_div_scale_f32 v30, vcc, v46, v26, v46
	v_mul_f32_e32 v31, v30, v45
	v_fma_f32 v47, -v44, v31, v30
	v_fmac_f32_e32 v31, v47, v45
	v_fma_f32 v30, -v44, v31, v30
	v_div_fmas_f32 v30, v30, v45, v31
	v_div_fixup_f32 v26, v30, v26, v46
	v_pk_mul_f32 v[30:31], v[54:55], v[0:1] op_sel_hi:[1,0]
	s_waitcnt vmcnt(0) lgkmcnt(0)
	v_pk_mul_f32 v[2:3], v[30:31], v[2:3]
	s_nop 0
	v_pk_mul_f32 v[2:3], v[2:3], v[24:25]
	v_pk_mul_f32 v[24:25], v[52:53], v[0:1] op_sel_hi:[1,0]
	v_cvt_pk_bf16_f32 v2, v2, v3
	v_pk_mul_f32 v[4:5], v[24:25], v[4:5]
	v_lshlrev_b32_e32 v30, 16, v28
	v_pk_mul_f32 v[4:5], v[4:5], v[26:27]
	v_and_b32_e32 v28, 0xffff0000, v28
	v_cvt_pk_bf16_f32 v3, v4, v5
	v_mov_b32_e32 v156, v2
	v_mov_b32_e32 v157, v3
	flat_load_dwordx4 v[2:5], v[6:7] offset:288
	v_mul_f32_e32 v24, 0xbfb8aa3b, v30
	v_mul_f32_e32 v25, 0xbfb8aa3b, v28
	v_exp_f32_e32 v24, v24
	v_exp_f32_e32 v25, v25
	flat_load_dwordx2 v[26:27], v[14:15] offset:160
	v_and_b32_e32 v52, 0xffff0000, v29
	v_pk_add_f32 v[24:25], v[24:25], 1.0 op_sel_hi:[1,0]
	s_nop 0
	v_div_scale_f32 v31, s[0:1], v25, v25, v28
	v_rcp_f32_e32 v44, v31
	s_nop 0
	v_fma_f32 v45, -v31, v44, 1.0
	v_fmac_f32_e32 v44, v45, v44
	v_div_scale_f32 v45, vcc, v28, v25, v28
	v_mul_f32_e32 v46, v45, v44
	v_fma_f32 v47, -v31, v46, v45
	v_fmac_f32_e32 v46, v47, v44
	v_fma_f32 v31, -v31, v46, v45
	v_div_scale_f32 v45, s[0:1], v24, v24, v30
	v_rcp_f32_e32 v47, v45
	v_div_fmas_f32 v31, v31, v44, v46
	v_div_fixup_f32 v25, v31, v25, v28
	v_lshlrev_b32_e32 v46, 16, v29
	v_fma_f32 v28, -v45, v47, 1.0
	v_fmac_f32_e32 v47, v28, v47
	v_mul_f32_e32 v28, 0xbfb8aa3b, v46
	v_mul_f32_e32 v29, 0xbfb8aa3b, v52
	v_exp_f32_e32 v28, v28
	v_exp_f32_e32 v29, v29
	v_div_scale_f32 v31, vcc, v30, v24, v30
	v_mul_f32_e32 v44, v31, v47
	v_fma_f32 v53, -v45, v44, v31
	v_fmac_f32_e32 v44, v53, v47
	v_pk_add_f32 v[28:29], v[28:29], 1.0 op_sel_hi:[1,0]
	v_fma_f32 v31, -v45, v44, v31
	v_div_scale_f32 v45, s[0:1], v29, v29, v52
	v_rcp_f32_e32 v53, v45
	v_div_fmas_f32 v31, v31, v47, v44
	v_div_fixup_f32 v24, v31, v24, v30
	v_fma_f32 v30, -v45, v53, 1.0
	v_fmac_f32_e32 v53, v30, v53
	v_div_scale_f32 v30, vcc, v52, v29, v52
	v_mul_f32_e32 v31, v30, v53
	v_fma_f32 v44, -v45, v31, v30
	v_fmac_f32_e32 v31, v44, v53
	v_div_scale_f32 v44, s[0:1], v28, v28, v46
	v_fma_f32 v30, -v45, v31, v30
	v_rcp_f32_e32 v45, v44
	v_div_fmas_f32 v30, v30, v53, v31
	v_div_fixup_f32 v29, v30, v29, v52
	v_fma_f32 v30, -v44, v45, 1.0
	v_fmac_f32_e32 v45, v30, v45
	v_div_scale_f32 v30, vcc, v46, v28, v46
	v_mul_f32_e32 v31, v30, v45
	v_fma_f32 v47, -v44, v31, v30
	v_fmac_f32_e32 v31, v47, v45
	v_fma_f32 v30, -v44, v31, v30
	v_div_fmas_f32 v30, v30, v45, v31
	v_div_fixup_f32 v28, v30, v28, v46
	v_pk_mul_f32 v[30:31], v[50:51], v[0:1] op_sel_hi:[1,0]
	s_waitcnt vmcnt(0) lgkmcnt(0)
; DI unsigned pk2(float lo, float hi) { fl2_t f = {lo, hi}; bf2_t b = __builtin_convertvector(f, bf2_t); return __builtin_bit_cast(unsigned, b); }
; DI float bflo(unsigned u) { return __uint_as_float(u << 16); }
; DI float bfhi(unsigned u) { return __uint_as_float(u & 0xffff0000u); }
; DI float silu_f(float z) { return z / (1.f + __expf(-z)); }
; DI void diff_item(const Params& P, char* lds, int layer, int pair, int qt, int& tab_head) {
;     ...
;                 const int d = 32 * dt + 8 * g + 4 * hh;
;                 u32x2 zz = *(const u32x2*)(orow + OFF_Z + 1536 + head * 128 + d);
;                 f32x4 gg = *(const f32x4*)(gs + d);
;                 float y0 = O[dt][4 * g + 0] * rstd * gg.x * silu_f(bflo(zz.x)), y1 = O[dt][4 * g + 1] * rstd * gg.y * silu_f(bfhi(zz.x));
;                 float y2 = O[dt][4 * g + 2] * rstd * gg.z * silu_f(bflo(zz.y)), y3 = O[dt][4 * g + 3] * rstd * gg.w * silu_f(bfhi(zz.y));
;                 u32x2 o = {pk2(y0, y1), pk2(y2, y3)};
;                 *(u32x2*)(orow + OFF_CQ + head * 128 + d) = o;
	v_and_b32_e32 v46, 0xffff0000, v27
	v_pk_mul_f32 v[2:3], v[30:31], v[2:3]
	s_nop 0
	v_pk_mul_f32 v[2:3], v[2:3], v[24:25]
	v_pk_mul_f32 v[24:25], v[48:49], v[0:1] op_sel_hi:[1,0]
	v_cvt_pk_bf16_f32 v2, v2, v3
	v_pk_mul_f32 v[4:5], v[24:25], v[4:5]
	s_nop 0
	v_pk_mul_f32 v[4:5], v[4:5], v[28:29]
	v_lshlrev_b32_e32 v28, 16, v26
	v_cvt_pk_bf16_f32 v3, v4, v5
	v_mov_b32_e32 v158, v2
	v_mov_b32_e32 v159, v3
	s_nop 1
	v_permlane32_swap_b32_e32 v156, v158
	v_permlane32_swap_b32_e32 v157, v159
	s_nop 1
	global_store_dwordx4 v[160:161], v[156:159], off offset:128
	flat_load_dwordx4 v[2:5], v[6:7] offset:320
	v_and_b32_e32 v26, 0xffff0000, v26
	v_mul_f32_e32 v24, 0xbfb8aa3b, v28
	v_mul_f32_e32 v25, 0xbfb8aa3b, v26
	v_exp_f32_e32 v24, v24
	v_exp_f32_e32 v25, v25
	s_nop 0
	v_pk_add_f32 v[24:25], v[24:25], 1.0 op_sel_hi:[1,0]
	s_nop 0
	v_div_scale_f32 v29, s[0:1], v25, v25, v26
	v_rcp_f32_e32 v30, v29
	s_nop 0
	v_fma_f32 v31, -v29, v30, 1.0
	v_fmac_f32_e32 v30, v31, v30
	v_div_scale_f32 v31, vcc, v26, v25, v26
	v_mul_f32_e32 v44, v31, v30
	v_fma_f32 v45, -v29, v44, v31
	v_fmac_f32_e32 v44, v45, v30
	v_fma_f32 v29, -v29, v44, v31
	v_div_scale_f32 v31, s[0:1], v24, v24, v28
	v_rcp_f32_e32 v45, v31
	v_div_fmas_f32 v29, v29, v30, v44
	v_div_fixup_f32 v25, v29, v25, v26
	v_lshlrev_b32_e32 v30, 16, v27
	v_fma_f32 v26, -v31, v45, 1.0
	v_fmac_f32_e32 v45, v26, v45
	v_mul_f32_e32 v26, 0xbfb8aa3b, v30
	v_mul_f32_e32 v27, 0xbfb8aa3b, v46
	v_exp_f32_e32 v26, v26
	v_exp_f32_e32 v27, v27
	v_div_scale_f32 v29, vcc, v28, v24, v28
	v_mul_f32_e32 v44, v29, v45
	v_fma_f32 v47, -v31, v44, v29
	v_fmac_f32_e32 v44, v47, v45
	v_pk_add_f32 v[26:27], v[26:27], 1.0 op_sel_hi:[1,0]
	v_fma_f32 v29, -v31, v44, v29
	v_div_scale_f32 v31, s[0:1], v27, v27, v46
	v_rcp_f32_e32 v47, v31
	v_div_fmas_f32 v29, v29, v45, v44
	v_div_fixup_f32 v24, v29, v24, v28
	v_fma_f32 v28, -v31, v47, 1.0
	v_fmac_f32_e32 v47, v28, v47
	v_div_scale_f32 v28, vcc, v46, v27, v46
	v_mul_f32_e32 v29, v28, v47
	v_fma_f32 v44, -v31, v29, v28
	v_fmac_f32_e32 v29, v44, v47
	v_div_scale_f32 v44, s[0:1], v26, v26, v30
	v_fma_f32 v28, -v31, v29, v28
	v_rcp_f32_e32 v31, v44
	v_div_fmas_f32 v28, v28, v47, v29
	v_div_fixup_f32 v27, v28, v27, v46
	v_div_scale_f32 v46, vcc, v30, v26, v30
	v_fma_f32 v28, -v44, v31, 1.0
	v_fmac_f32_e32 v31, v28, v31
	v_mul_f32_e32 v45, v46, v31
	flat_load_dwordx2 v[28:29], v[14:15] offset:176
	v_fma_f32 v47, -v44, v45, v46
	v_fmac_f32_e32 v45, v47, v31
	v_fma_f32 v44, -v44, v45, v46
	v_div_fmas_f32 v31, v44, v31, v45
	v_div_fixup_f32 v26, v31, v26, v30
	v_pk_mul_f32 v[30:31], v[40:41], v[0:1] op_sel_hi:[1,0]
	s_waitcnt vmcnt(0) lgkmcnt(0)
	v_pk_mul_f32 v[2:3], v[30:31], v[2:3]
	s_nop 0
	v_pk_mul_f32 v[2:3], v[2:3], v[24:25]
	v_pk_mul_f32 v[24:25], v[42:43], v[0:1] op_sel_hi:[1,0]
	v_cvt_pk_bf16_f32 v2, v2, v3
	v_pk_mul_f32 v[4:5], v[24:25], v[4:5]
	v_lshlrev_b32_e32 v30, 16, v28
	v_pk_mul_f32 v[4:5], v[4:5], v[26:27]
	v_and_b32_e32 v28, 0xffff0000, v28
	v_cvt_pk_bf16_f32 v3, v4, v5
	v_mov_b32_e32 v156, v2
	v_mov_b32_e32 v157, v3
	flat_load_dwordx4 v[2:5], v[6:7] offset:352
	v_mul_f32_e32 v24, 0xbfb8aa3b, v30
	v_mul_f32_e32 v25, 0xbfb8aa3b, v28
	v_exp_f32_e32 v24, v24
	v_exp_f32_e32 v25, v25
	v_pk_mul_f32 v[26:27], v[38:39], v[0:1] op_sel_hi:[1,0]
	v_lshlrev_b32_e32 v39, 16, v29
	v_and_b32_e32 v29, 0xffff0000, v29
	v_pk_add_f32 v[24:25], v[24:25], 1.0 op_sel_hi:[1,0]
	s_waitcnt vmcnt(0) lgkmcnt(0)
	v_pk_mul_f32 v[2:3], v[26:27], v[2:3]
	v_div_scale_f32 v31, s[0:1], v25, v25, v28
	v_rcp_f32_e32 v40, v31
	s_nop 0
	v_fma_f32 v26, -v31, v40, 1.0
	v_fmac_f32_e32 v40, v26, v40
	v_div_scale_f32 v26, vcc, v28, v25, v28
	v_mul_f32_e32 v27, v26, v40
	v_fma_f32 v38, -v31, v27, v26
	v_fmac_f32_e32 v27, v38, v40
	v_fma_f32 v26, -v31, v27, v26
	v_div_scale_f32 v31, s[0:1], v24, v24, v30
	v_rcp_f32_e32 v38, v31
	v_div_fmas_f32 v26, v26, v40, v27
	v_div_fixup_f32 v25, v26, v25, v28
	v_fma_f32 v26, -v31, v38, 1.0
	v_fmac_f32_e32 v38, v26, v38
	v_div_scale_f32 v26, vcc, v30, v24, v30
	v_mul_f32_e32 v28, v26, v38
	v_fma_f32 v27, -v31, v28, v26
	v_fmac_f32_e32 v28, v27, v38
	v_fma_f32 v31, -v31, v28, v26
	v_mul_f32_e32 v26, 0xbfb8aa3b, v39
	v_mul_f32_e32 v27, 0xbfb8aa3b, v29
	v_exp_f32_e32 v26, v26
	v_exp_f32_e32 v27, v27
	v_div_fmas_f32 v28, v31, v38, v28
	v_div_fixup_f32 v24, v28, v24, v30
	v_pk_mul_f32 v[2:3], v[2:3], v[24:25]
	v_pk_add_f32 v[26:27], v[26:27], 1.0 op_sel_hi:[1,0]
	v_pk_mul_f32 v[24:25], v[36:37], v[0:1] op_sel_hi:[1,0]
	v_div_scale_f32 v28, s[0:1], v27, v27, v29
	v_rcp_f32_e32 v30, v28
	v_pk_mul_f32 v[4:5], v[24:25], v[4:5]
	v_cvt_pk_bf16_f32 v2, v2, v3
	v_fma_f32 v24, -v28, v30, 1.0
	v_fmac_f32_e32 v30, v24, v30
	v_div_scale_f32 v24, vcc, v29, v27, v29
	v_mul_f32_e32 v25, v24, v30
	v_fma_f32 v31, -v28, v25, v24
	v_fmac_f32_e32 v25, v31, v30
	v_div_scale_f32 v31, s[0:1], v26, v26, v39
	v_rcp_f32_e32 v36, v31
	v_fma_f32 v24, -v28, v25, v24
	v_div_fmas_f32 v24, v24, v30, v25
	v_div_fixup_f32 v25, v24, v27, v29
	flat_load_dwordx2 v[28:29], v[14:15] offset:192
	v_fma_f32 v24, -v31, v36, 1.0
	v_fmac_f32_e32 v36, v24, v36
	v_div_scale_f32 v24, vcc, v39, v26, v39
	v_mul_f32_e32 v27, v24, v36
	v_fma_f32 v30, -v31, v27, v24
	v_fmac_f32_e32 v27, v30, v36
	v_fma_f32 v24, -v31, v27, v24
	v_div_fmas_f32 v24, v24, v36, v27
	v_div_fixup_f32 v24, v24, v26, v39
	v_pk_mul_f32 v[4:5], v[4:5], v[24:25]
	s_waitcnt vmcnt(0) lgkmcnt(0)
; DI unsigned pk2(float lo, float hi) { fl2_t f = {lo, hi}; bf2_t b = __builtin_convertvector(f, bf2_t); return __builtin_bit_cast(unsigned, b); }
; DI float bflo(unsigned u) { return __uint_as_float(u << 16); }
; DI float bfhi(unsigned u) { return __uint_as_float(u & 0xffff0000u); }
; DI float silu_f(float z) { return z / (1.f + __expf(-z)); }
; DI void diff_item(const Params& P, char* lds, int layer, int pair, int qt, int& tab_head) {
;     ...
;                 const int d = 32 * dt + 8 * g + 4 * hh;
;                 u32x2 zz = *(const u32x2*)(orow + OFF_Z + 1536 + head * 128 + d);
;                 f32x4 gg = *(const f32x4*)(gs + d);
;                 float y0 = O[dt][4 * g + 0] * rstd * gg.x * silu_f(bflo(zz.x)), y1 = O[dt][4 * g + 1] * rstd * gg.y * silu_f(bfhi(zz.x));
;                 float y2 = O[dt][4 * g + 2] * rstd * gg.z * silu_f(bflo(zz.y)), y3 = O[dt][4 * g + 3] * rstd * gg.w * silu_f(bfhi(zz.y));
;                 u32x2 o = {pk2(y0, y1), pk2(y2, y3)};
;                 *(u32x2*)(orow + OFF_CQ + head * 128 + d) = o;
	v_lshlrev_b32_e32 v30, 16, v28
	v_cvt_pk_bf16_f32 v3, v4, v5
	v_mov_b32_e32 v158, v2
	v_mov_b32_e32 v159, v3
	s_nop 1
	v_permlane32_swap_b32_e32 v156, v158
	v_permlane32_swap_b32_e32 v157, v159
	s_nop 1
	global_store_dwordx4 v[160:161], v[156:159], off offset:160
	flat_load_dwordx4 v[24:27], v[6:7] offset:384
	v_and_b32_e32 v28, 0xffff0000, v28
	v_mul_f32_e32 v2, 0xbfb8aa3b, v30
	v_mul_f32_e32 v3, 0xbfb8aa3b, v28
	v_exp_f32_e32 v2, v2
	v_exp_f32_e32 v3, v3
	v_pk_mul_f32 v[4:5], v[34:35], v[0:1] op_sel_hi:[1,0]
	v_and_b32_e32 v35, 0xffff0000, v29
	v_pk_add_f32 v[2:3], v[2:3], 1.0 op_sel_hi:[1,0]
	s_nop 0
	v_div_scale_f32 v31, s[0:1], v3, v3, v28
	v_rcp_f32_e32 v36, v31
	s_waitcnt vmcnt(0) lgkmcnt(0)
	v_pk_mul_f32 v[4:5], v[4:5], v[24:25]
	v_fma_f32 v24, -v31, v36, 1.0
	v_fmac_f32_e32 v36, v24, v36
	v_div_scale_f32 v24, vcc, v28, v3, v28
	v_mul_f32_e32 v25, v24, v36
	v_fma_f32 v34, -v31, v25, v24
	v_fmac_f32_e32 v25, v34, v36
	v_fma_f32 v24, -v31, v25, v24
	v_div_scale_f32 v31, s[0:1], v2, v2, v30
	v_rcp_f32_e32 v34, v31
	v_div_fmas_f32 v24, v24, v36, v25
	v_div_fixup_f32 v25, v24, v3, v28
	v_fma_f32 v3, -v31, v34, 1.0
	v_fmac_f32_e32 v34, v3, v34
	v_div_scale_f32 v3, vcc, v30, v2, v30
	v_mul_f32_e32 v24, v3, v34
	v_fma_f32 v28, -v31, v24, v3
	v_fmac_f32_e32 v24, v28, v34
	v_fma_f32 v3, -v31, v24, v3
	v_lshlrev_b32_e32 v31, 16, v29
	v_mul_f32_e32 v28, 0xbfb8aa3b, v31
	v_mul_f32_e32 v29, 0xbfb8aa3b, v35
	v_exp_f32_e32 v28, v28
	v_exp_f32_e32 v29, v29
	v_div_fmas_f32 v3, v3, v34, v24
	v_div_fixup_f32 v24, v3, v2, v30
	v_pk_mul_f32 v[4:5], v[4:5], v[24:25]
	v_pk_add_f32 v[2:3], v[28:29], 1.0 op_sel_hi:[1,0]
	v_pk_mul_f32 v[24:25], v[32:33], v[0:1] op_sel_hi:[1,0]
	v_div_scale_f32 v28, s[0:1], v3, v3, v35
	v_rcp_f32_e32 v29, v28
	v_pk_mul_f32 v[24:25], v[24:25], v[26:27]
	v_cvt_pk_bf16_f32 v4, v4, v5
	v_fma_f32 v26, -v28, v29, 1.0
	v_fmac_f32_e32 v29, v26, v29
	v_div_scale_f32 v26, vcc, v35, v3, v35
	v_mul_f32_e32 v27, v26, v29
	v_fma_f32 v30, -v28, v27, v26
	v_fmac_f32_e32 v27, v30, v29
	v_fma_f32 v26, -v28, v27, v26
	v_div_scale_f32 v30, s[0:1], v2, v2, v31
	v_rcp_f32_e32 v32, v30
	v_div_fmas_f32 v26, v26, v29, v27
	flat_load_dwordx2 v[28:29], v[14:15] offset:208
	v_div_fixup_f32 v3, v26, v3, v35
	v_fma_f32 v26, -v30, v32, 1.0
	v_fmac_f32_e32 v32, v26, v32
	v_div_scale_f32 v26, vcc, v31, v2, v31
	v_mul_f32_e32 v27, v26, v32
	v_fma_f32 v33, -v30, v27, v26
	v_fmac_f32_e32 v27, v33, v32
	v_fma_f32 v26, -v30, v27, v26
	v_div_fmas_f32 v26, v26, v32, v27
	v_div_fixup_f32 v2, v26, v2, v31
	v_pk_mul_f32 v[2:3], v[24:25], v[2:3]
	s_waitcnt vmcnt(0) lgkmcnt(0)
	v_lshlrev_b32_e32 v30, 16, v28
	v_cvt_pk_bf16_f32 v5, v2, v3
	v_mov_b32_e32 v156, v4
	v_mov_b32_e32 v157, v5
	flat_load_dwordx4 v[24:27], v[6:7] offset:416
	v_and_b32_e32 v28, 0xffff0000, v28
	v_mul_f32_e32 v2, 0xbfb8aa3b, v30
	v_mul_f32_e32 v3, 0xbfb8aa3b, v28
	v_exp_f32_e32 v2, v2
	v_exp_f32_e32 v3, v3
	v_pk_mul_f32 v[4:5], v[20:21], v[0:1] op_sel_hi:[1,0]
	v_pk_add_f32 v[2:3], v[2:3], 1.0 op_sel_hi:[1,0]
	s_nop 0
	v_div_scale_f32 v31, s[0:1], v3, v3, v28
	v_rcp_f32_e32 v32, v31
	s_waitcnt vmcnt(0) lgkmcnt(0)
	v_pk_mul_f32 v[4:5], v[4:5], v[24:25]
	v_fma_f32 v20, -v31, v32, 1.0
	v_fmac_f32_e32 v32, v20, v32
	v_div_scale_f32 v20, vcc, v28, v3, v28
	v_mul_f32_e32 v21, v20, v32
	v_fma_f32 v24, -v31, v21, v20
	v_fmac_f32_e32 v21, v24, v32
	v_div_scale_f32 v24, s[0:1], v2, v2, v30
	v_fma_f32 v20, -v31, v21, v20
	v_rcp_f32_e32 v31, v24
	v_div_fmas_f32 v20, v20, v32, v21
	v_div_fixup_f32 v21, v20, v3, v28
	v_lshlrev_b32_e32 v28, 16, v29
	v_fma_f32 v3, -v24, v31, 1.0
	v_fmac_f32_e32 v31, v3, v31
	v_div_scale_f32 v3, vcc, v30, v2, v30
	v_mul_f32_e32 v20, v3, v31
	v_fma_f32 v25, -v24, v20, v3
	v_fmac_f32_e32 v20, v25, v31
	v_and_b32_e32 v29, 0xffff0000, v29
	v_fma_f32 v3, -v24, v20, v3
	v_mul_f32_e32 v24, 0xbfb8aa3b, v28
	v_mul_f32_e32 v25, 0xbfb8aa3b, v29
	v_exp_f32_e32 v24, v24
	v_exp_f32_e32 v25, v25
	v_div_fmas_f32 v3, v3, v31, v20
	v_div_fixup_f32 v20, v3, v2, v30
	v_pk_mul_f32 v[4:5], v[4:5], v[20:21]
	v_pk_add_f32 v[2:3], v[24:25], 1.0 op_sel_hi:[1,0]
	v_pk_mul_f32 v[20:21], v[22:23], v[0:1] op_sel_hi:[1,0]
	v_div_scale_f32 v24, s[0:1], v3, v3, v29
	v_rcp_f32_e32 v25, v24
	v_pk_mul_f32 v[20:21], v[20:21], v[26:27]
	v_cvt_pk_bf16_f32 v4, v4, v5
	v_fma_f32 v22, -v24, v25, 1.0
	v_fmac_f32_e32 v25, v22, v25
	v_div_scale_f32 v22, vcc, v29, v3, v29
	v_mul_f32_e32 v23, v22, v25
	v_fma_f32 v26, -v24, v23, v22
	v_fmac_f32_e32 v23, v26, v25
	v_div_scale_f32 v26, s[0:1], v2, v2, v28
	v_rcp_f32_e32 v27, v26
	v_fma_f32 v22, -v24, v23, v22
	v_div_fmas_f32 v22, v22, v25, v23
	flat_load_dwordx2 v[24:25], v[14:15] offset:224
	v_div_fixup_f32 v3, v22, v3, v29
	v_fma_f32 v22, -v26, v27, 1.0
	v_fmac_f32_e32 v27, v22, v27
	v_div_scale_f32 v22, vcc, v28, v2, v28
	v_mul_f32_e32 v23, v22, v27
	v_fma_f32 v29, -v26, v23, v22
	v_fmac_f32_e32 v23, v29, v27
	v_fma_f32 v22, -v26, v23, v22
	v_div_fmas_f32 v22, v22, v27, v23
	v_div_fixup_f32 v2, v22, v2, v28
	v_pk_mul_f32 v[2:3], v[20:21], v[2:3]
	s_waitcnt vmcnt(0) lgkmcnt(0)
; DI unsigned pk2(float lo, float hi) { fl2_t f = {lo, hi}; bf2_t b = __builtin_convertvector(f, bf2_t); return __builtin_bit_cast(unsigned, b); }
; DI float bflo(unsigned u) { return __uint_as_float(u << 16); }
; DI float bfhi(unsigned u) { return __uint_as_float(u & 0xffff0000u); }
; DI float silu_f(float z) { return z / (1.f + __expf(-z)); }
; DI void diff_item(const Params& P, char* lds, int layer, int pair, int qt, int& tab_head) {
;     ...
;                 const int d = 32 * dt + 8 * g + 4 * hh;
;                 u32x2 zz = *(const u32x2*)(orow + OFF_Z + 1536 + head * 128 + d);
;                 f32x4 gg = *(const f32x4*)(gs + d);
;                 float y0 = O[dt][4 * g + 0] * rstd * gg.x * silu_f(bflo(zz.x)), y1 = O[dt][4 * g + 1] * rstd * gg.y * silu_f(bfhi(zz.x));
;                 float y2 = O[dt][4 * g + 2] * rstd * gg.z * silu_f(bflo(zz.y)), y3 = O[dt][4 * g + 3] * rstd * gg.w * silu_f(bfhi(zz.y));
;                 u32x2 o = {pk2(y0, y1), pk2(y2, y3)};
;                 *(u32x2*)(orow + OFF_CQ + head * 128 + d) = o;
	v_lshlrev_b32_e32 v26, 16, v24
	v_cvt_pk_bf16_f32 v5, v2, v3
	v_mov_b32_e32 v158, v4
	v_mov_b32_e32 v159, v5
	s_nop 1
	v_permlane32_swap_b32_e32 v156, v158
	v_permlane32_swap_b32_e32 v157, v159
	s_nop 1
	global_store_dwordx4 v[160:161], v[156:159], off offset:192
	flat_load_dwordx4 v[20:23], v[6:7] offset:448
	v_and_b32_e32 v24, 0xffff0000, v24
	v_mul_f32_e32 v2, 0xbfb8aa3b, v26
	v_mul_f32_e32 v3, 0xbfb8aa3b, v24
	v_exp_f32_e32 v2, v2
	v_exp_f32_e32 v3, v3
	v_pk_mul_f32 v[4:5], v[18:19], v[0:1] op_sel_hi:[1,0]
	v_pk_add_f32 v[2:3], v[2:3], 1.0 op_sel_hi:[1,0]
	s_nop 0
	v_div_scale_f32 v27, s[0:1], v3, v3, v24
	v_rcp_f32_e32 v28, v27
	s_waitcnt vmcnt(0) lgkmcnt(0)
	v_pk_mul_f32 v[18:19], v[4:5], v[20:21]
	v_fma_f32 v4, -v27, v28, 1.0
	v_fmac_f32_e32 v28, v4, v28
	v_div_scale_f32 v4, vcc, v24, v3, v24
	v_mul_f32_e32 v5, v4, v28
	v_fma_f32 v20, -v27, v5, v4
	v_fmac_f32_e32 v5, v20, v28
	v_div_scale_f32 v20, s[0:1], v2, v2, v26
	v_rcp_f32_e32 v21, v20
	v_fma_f32 v4, -v27, v5, v4
	v_div_fmas_f32 v4, v4, v28, v5
	v_div_fixup_f32 v3, v4, v3, v24
	v_fma_f32 v4, -v20, v21, 1.0
	v_fmac_f32_e32 v21, v4, v21
	v_div_scale_f32 v4, vcc, v26, v2, v26
	v_mul_f32_e32 v24, v4, v21
	v_fma_f32 v5, -v20, v24, v4
	v_fmac_f32_e32 v24, v5, v21
	v_fma_f32 v27, -v20, v24, v4
	v_lshlrev_b32_e32 v20, 16, v25
	v_and_b32_e32 v25, 0xffff0000, v25
	v_mul_f32_e32 v4, 0xbfb8aa3b, v20
	v_mul_f32_e32 v5, 0xbfb8aa3b, v25
	v_exp_f32_e32 v4, v4
	v_exp_f32_e32 v5, v5
	v_div_fmas_f32 v21, v27, v21, v24
	v_div_fixup_f32 v2, v21, v2, v26
	v_pk_mul_f32 v[18:19], v[18:19], v[2:3]
	v_pk_add_f32 v[4:5], v[4:5], 1.0 op_sel_hi:[1,0]
	v_pk_mul_f32 v[2:3], v[16:17], v[0:1] op_sel_hi:[1,0]
	v_div_scale_f32 v21, s[0:1], v5, v5, v25
	v_rcp_f32_e32 v24, v21
	v_pk_mul_f32 v[16:17], v[2:3], v[22:23]
	v_fma_f32 v2, -v21, v24, 1.0
	v_fmac_f32_e32 v24, v2, v24
	v_div_scale_f32 v2, vcc, v25, v5, v25
	v_mul_f32_e32 v3, v2, v24
	v_fma_f32 v22, -v21, v3, v2
	v_fmac_f32_e32 v3, v22, v24
	v_div_scale_f32 v22, s[0:1], v4, v4, v20
	v_fma_f32 v2, -v21, v3, v2
	v_rcp_f32_e32 v21, v22
	v_div_fmas_f32 v2, v2, v24, v3
	v_div_fixup_f32 v5, v2, v5, v25
	flat_load_dwordx2 v[2:3], v[14:15] offset:240
	v_fma_f32 v23, -v22, v21, 1.0
	v_fmac_f32_e32 v21, v23, v21
	v_div_scale_f32 v14, vcc, v20, v4, v20
	v_mul_f32_e32 v15, v14, v21
	v_fma_f32 v23, -v22, v15, v14
	v_fmac_f32_e32 v15, v23, v21
	v_fma_f32 v14, -v22, v15, v14
	v_div_fmas_f32 v14, v14, v21, v15
	v_div_fixup_f32 v4, v14, v4, v20
	v_pk_mul_f32 v[4:5], v[16:17], v[4:5]
	v_cvt_pk_bf16_f32 v14, v18, v19
	v_cvt_pk_bf16_f32 v15, v4, v5
	v_mov_b32_e32 v156, v14
	v_mov_b32_e32 v157, v15
	flat_load_dwordx4 v[4:7], v[6:7] offset:480
	s_waitcnt vmcnt(0) lgkmcnt(0)
	v_lshlrev_b32_e32 v16, 16, v2
	v_and_b32_e32 v2, 0xffff0000, v2
	v_mul_f32_e32 v14, 0xbfb8aa3b, v16
	v_mul_f32_e32 v15, 0xbfb8aa3b, v2
	v_exp_f32_e32 v14, v14
	v_exp_f32_e32 v15, v15
	v_pk_mul_f32 v[4:5], v[12:13], v[4:5]
	v_pk_add_f32 v[14:15], v[14:15], 1.0 op_sel_hi:[1,0]
	v_pk_mul_f32 v[6:7], v[10:11], v[6:7]
	v_div_scale_f32 v17, s[0:1], v15, v15, v2
	v_rcp_f32_e32 v18, v17
	s_nop 0
	v_fma_f32 v12, -v17, v18, 1.0
	v_fmac_f32_e32 v18, v12, v18
	v_div_scale_f32 v12, vcc, v2, v15, v2
	v_mul_f32_e32 v13, v12, v18
	v_fma_f32 v19, -v17, v13, v12
	v_fmac_f32_e32 v13, v19, v18
	v_fma_f32 v12, -v17, v13, v12
	v_div_scale_f32 v17, s[0:1], v14, v14, v16
	v_rcp_f32_e32 v19, v17
	v_div_fmas_f32 v12, v12, v18, v13
	v_div_fixup_f32 v13, v12, v15, v2
	v_and_b32_e32 v18, 0xffff0000, v3
	v_fma_f32 v2, -v17, v19, 1.0
	v_fmac_f32_e32 v19, v2, v19
	v_div_scale_f32 v2, vcc, v16, v14, v16
	v_mul_f32_e32 v12, v2, v19
	v_fma_f32 v15, -v17, v12, v2
	v_fmac_f32_e32 v12, v15, v19
	v_fma_f32 v15, -v17, v12, v2
	v_lshlrev_b32_e32 v17, 16, v3
	v_mul_f32_e32 v2, 0xbfb8aa3b, v17
	v_mul_f32_e32 v3, 0xbfb8aa3b, v18
	v_exp_f32_e32 v2, v2
	v_exp_f32_e32 v3, v3
	v_div_fmas_f32 v12, v15, v19, v12
	v_div_fixup_f32 v12, v12, v14, v16
	v_pk_mul_f32 v[4:5], v[4:5], v[12:13]
	v_pk_add_f32 v[2:3], v[2:3], 1.0 op_sel_hi:[1,0]
	v_cvt_pk_bf16_f32 v4, v4, v5
	v_div_scale_f32 v14, s[0:1], v3, v3, v18
	v_rcp_f32_e32 v15, v14
	s_nop 0
	v_fma_f32 v0, -v14, v15, 1.0
	v_fmac_f32_e32 v15, v0, v15
	v_div_scale_f32 v0, vcc, v18, v3, v18
	v_mul_f32_e32 v10, v0, v15
	v_fma_f32 v11, -v14, v10, v0
	v_fmac_f32_e32 v10, v11, v15
	v_div_scale_f32 v11, s[0:1], v2, v2, v17
	v_rcp_f32_e32 v12, v11
	v_fma_f32 v0, -v14, v10, v0
	v_div_fmas_f32 v0, v0, v15, v10
	v_div_fixup_f32 v3, v0, v3, v18
	v_fma_f32 v0, -v11, v12, 1.0
	v_fmac_f32_e32 v12, v0, v12
	v_div_scale_f32 v0, vcc, v17, v2, v17
	v_mul_f32_e32 v10, v0, v12
	v_fma_f32 v13, -v11, v10, v0
	v_fmac_f32_e32 v10, v13, v12
	v_fma_f32 v0, -v11, v10, v0
	v_div_fmas_f32 v0, v0, v12, v10
	v_div_fixup_f32 v2, v0, v2, v17
	v_pk_mul_f32 v[2:3], v[6:7], v[2:3]
	s_nop 0
	v_cvt_pk_bf16_f32 v5, v2, v3
	v_mov_b32_e32 v158, v4
	v_mov_b32_e32 v159, v5
	s_nop 1
	v_permlane32_swap_b32_e32 v156, v158
	v_permlane32_swap_b32_e32 v157, v159
	s_nop 1
	global_store_dwordx4 v[160:161], v[156:159], off offset:224
	s_branch .LBB0_197
